# GEMM tiles: accumulator zeroing (128 v_mov per tile header) replaced by a peeled first half-iteration whose first MFMA per accumulator takes C=0; on top of the v133 stack
# speedup vs baseline: 1.0263x; 1.0263x over previous
; #define PG8_STAGE(bufoff, gbase, voff) do { _Pragma("unroll") for (int _i = 0; _i < 2; ++_i) \
;         __builtin_amdgcn_global_load_lds((const unsigned*)((const char*)(gbase) + (voff)[_i]), (PG8_LAS unsigned*)(lds + (bufoff) + ldsw + _i * 8192), 16, 0, 0); } while (0)
; #define PG8_LDA(dst, b, h) do { _Pragma("unroll") for (int m = 0; m < 4; ++m) _Pragma("unroll") for (int k = 0; k < 2; ++k) dst[m][k] = *(const PG8_LAS bf16x8*)(lds + PG8_SA(b, h) + aoff + m * 2048 + k * 1024); } while (0)
; #define PG8_LDB(dst, b, h) do { _Pragma("unroll") for (int n = 0; n < 2; ++n) _Pragma("unroll") for (int k = 0; k < 2; ++k) dst[n][k] = *(const PG8_LAS bf16x8*)(lds + PG8_SB(b, h) + boff + n * 2048 + k * 1024); } while (0)
; #define PG8_MMA(ai, bj, At, Bt) do { __builtin_amdgcn_s_setprio(1); _Pragma("unroll") for (int m = 0; m < 4; ++m) _Pragma("unroll") for (int n = 0; n < 2; ++n) _Pragma("unroll") for (int k = 0; k < 2; ++k) \
;         acc[ai][bj][m][n] = __builtin_amdgcn_mfma_f32_16x16x32_bf16(Bt[n][k], At[m][k], acc[ai][bj][m][n], 0, 0, 0); __builtin_amdgcn_s_setprio(0); } while (0)
; #define PG8_WAIT_V(n) asm volatile("s_waitcnt vmcnt(" #n ")" ::: "memory")
; #define PG8_WAIT_L(n) asm volatile("s_waitcnt lgkmcnt(" #n ")" ::: "memory")
; template <class Epi, class Sched, bool ALIGN_EPI = false, bool SP2 = false>
; __device__ __forceinline__ void gemm_phase(PG8_LAS unsigned char* lds, const Gemm g, const Sched& S, const Epi& E) {
;     ...
;         const bool has_next = S.next(ui + 1, nxt);
;         const char* nA = has_next ? (const char*)g.A + (size_t)nxt.pm * tstep : cA; const char* nB = has_next ? (const char*)g.Bt + (size_t)nxt.pn * tstep : cB;
;         for (int t = 0; t < nt; t += 2) {
;             const bool last = (t == nt - 2);
;             const char* a1 = cA + (size_t)(t + 1) * kstep;
;             const char* a2 = last ? nA : cA + (size_t)(t + 2) * kstep; const char* b2 = last ? nB : cB + (size_t)(t + 2) * kstep;
;             const char* a3 = a2 + kstep; const char* b3 = b2 + kstep;
;             if (last && has_next) S.a_ready(nxt);
;             if constexpr (SP2) {
;             PG8_LDB(B0, 0, 0); PG8_LDB(B1, 0, 1); PG8_SCHED; PG8_LDA(At, 0, 0); PG8_STAGE(PG8_SA(1, 0), a1, voffA); PG8_STAGE(PG8_SA(1, 1), a1 + hstep, voffA);
;             PG8_WAIT_V(8); PG8_WAIT_L(0); PG8_BAR; PG8_MMA(0, 0, At, B0); PG8_MMA(0, 1, At, B1); PG8_BAR; PG8_SCHED;
.LBB0_211:
	s_ashr_i32 s89, s88, 31
	s_lshl_b64 s[4:5], s[88:89], 20
	s_add_u32 s4, s22, s4
	s_addc_u32 s5, s75, s5
	s_and_b64 s[6:7], s[38:39], exec
	s_cselect_b32 s89, s5, s9
	s_cselect_b32 vcc_lo, s4, s8
	s_ashr_i32 s73, s72, 31
	s_lshl_b64 s[6:7], s[72:73], 20
	s_add_u32 s6, s68, s6
	s_addc_u32 s7, s69, s7
	s_and_b64 s[16:17], s[38:39], exec
	s_cselect_b32 s70, s7, s11
	s_cselect_b32 s71, s6, s10
	s_add_u32 s73, s10, 0x100
	s_addc_u32 vcc_hi, s11, 0
	s_mov_b32 s52, -2
	s_mov_b64 s[10:11], 0
	v_lshl_add_u64 v[138:139], s[8:9], 0, v[134:135]
	v_lshl_add_u64 v[140:141], s[8:9], 0, v[136:137]
	v_lshl_add_u32 v240, s35, 8, v146
	v_ashrrev_i32_e32 v241, 31, v240
	v_lshl_add_u64 v[240:241], v[240:241], 2, s[42:43]
	global_load_dword v242, v[240:241], off
	global_load_dword v243, v[240:241], off offset:64
	global_load_dword v244, v[240:241], off offset:128
	global_load_dword v245, v[240:241], off offset:192
	global_load_dword v246, v[240:241], off offset:512
	global_load_dword v247, v[240:241], off offset:576
	global_load_dword v248, v[240:241], off offset:640
	global_load_dword v249, v[240:241], off offset:704
	s_add_u32 s16, s8, s10
	s_addc_u32 s17, s9, s11
	s_add_u32 s44, s16, 0x100
	s_addc_u32 s45, s17, 0
	s_add_u32 s16, s73, s10
	s_addc_u32 s17, vcc_hi, s11
	s_add_i32 s53, 0, 0x10000
	s_cmpk_eq_i32 s10, 0xf00
	s_cselect_b32 s17, s70, s17
	s_cselect_b32 s16, s71, s16
	s_cselect_b32 s45, s89, s45
	s_cselect_b32 s44, vcc_lo, s44
	s_add_i32 s92, 0, 0x14000
	v_add_u32_e32 v158, s53, v147
	v_add_u32_e32 v174, s92, v147
	ds_read_b128 v[142:145], v158
	ds_read_b128 v[150:153], v158 offset:1024
	ds_read_b128 v[154:157], v158 offset:2048
	ds_read_b128 v[158:161], v158 offset:3072
	ds_read_b128 v[162:165], v174
	ds_read_b128 v[166:169], v174 offset:1024
	ds_read_b128 v[170:173], v174 offset:2048
	ds_read_b128 v[174:177], v174 offset:3072
	v_lshl_add_u64 v[202:203], v[138:139], 0, s[10:11]
	v_lshl_add_u64 v[206:207], v[202:203], 0, s[26:27]
	s_add_i32 m0, s97, 0x8000
	ds_read_b128 v[178:181], v149
	ds_read_b128 v[182:185], v149 offset:1024
	ds_read_b128 v[186:189], v149 offset:2048
	ds_read_b128 v[190:193], v149 offset:3072
	ds_read_b128 v[194:197], v149 offset:4096
	ds_read_b128 v[198:201], v149 offset:5120
	ds_read_b128 v[218:221], v149 offset:6144
	ds_read_b128 v[232:235], v149 offset:7168
	global_load_lds_dwordx4 v[206:207], off
	v_lshl_add_u64 v[206:207], v[140:141], 0, s[10:11]
	v_lshl_add_u64 v[208:209], v[206:207], 0, s[26:27]
	s_add_i32 m0, s97, 0xa000
	v_lshl_add_u64 v[202:203], v[202:203], 0, s[28:29]
	global_load_lds_dwordx4 v[208:209], off
	s_add_i32 m0, s97, 0xc000
	s_nop 0
	global_load_lds_dwordx4 v[202:203], off
	v_lshl_add_u64 v[202:203], v[206:207], 0, s[28:29]
	s_add_i32 m0, s97, 0xe000
	s_nop 0
	global_load_lds_dwordx4 v[202:203], off
	s_waitcnt vmcnt(8)
	s_waitcnt lgkmcnt(0)
	s_barrier
	v_mfma_f32_16x16x32_bf16 v[124:127], v[142:145], v[178:181], 0
	v_mfma_f32_16x16x32_bf16 v[120:123], v[154:157], v[178:181], 0
	v_mfma_f32_16x16x32_bf16 v[108:111], v[142:145], v[186:189], 0
	v_mfma_f32_16x16x32_bf16 v[104:107], v[154:157], v[186:189], 0
	v_mfma_f32_16x16x32_bf16 v[92:95], v[142:145], v[194:197], 0
	v_mfma_f32_16x16x32_bf16 v[88:91], v[154:157], v[194:197], 0
	v_mfma_f32_16x16x32_bf16 v[76:79], v[142:145], v[218:221], 0
	v_mfma_f32_16x16x32_bf16 v[72:75], v[154:157], v[218:221], 0
	v_mfma_f32_16x16x32_bf16 v[124:127], v[150:153], v[182:185], v[124:127]
	v_mfma_f32_16x16x32_bf16 v[120:123], v[158:161], v[182:185], v[120:123]
	v_mfma_f32_16x16x32_bf16 v[108:111], v[150:153], v[190:193], v[108:111]
	v_mfma_f32_16x16x32_bf16 v[104:107], v[158:161], v[190:193], v[104:107]
	v_mfma_f32_16x16x32_bf16 v[92:95], v[150:153], v[198:201], v[92:95]
	v_mfma_f32_16x16x32_bf16 v[88:91], v[158:161], v[198:201], v[88:91]
	v_mfma_f32_16x16x32_bf16 v[76:79], v[150:153], v[232:235], v[76:79]
	v_mfma_f32_16x16x32_bf16 v[72:75], v[158:161], v[232:235], v[72:75]
	v_mfma_f32_16x16x32_bf16 v[116:119], v[162:165], v[178:181], 0
	v_mfma_f32_16x16x32_bf16 v[112:115], v[170:173], v[178:181], 0
	v_mfma_f32_16x16x32_bf16 v[100:103], v[162:165], v[186:189], 0
	v_mfma_f32_16x16x32_bf16 v[96:99], v[170:173], v[186:189], 0
	v_mfma_f32_16x16x32_bf16 v[84:87], v[162:165], v[194:197], 0
	v_mfma_f32_16x16x32_bf16 v[80:83], v[170:173], v[194:197], 0
	v_mfma_f32_16x16x32_bf16 v[68:71], v[162:165], v[218:221], 0
	v_mfma_f32_16x16x32_bf16 v[64:67], v[170:173], v[218:221], 0
	v_mfma_f32_16x16x32_bf16 v[116:119], v[166:169], v[182:185], v[116:119]
	v_mfma_f32_16x16x32_bf16 v[112:115], v[174:177], v[182:185], v[112:115]
	v_mfma_f32_16x16x32_bf16 v[100:103], v[166:169], v[190:193], v[100:103]
	v_mfma_f32_16x16x32_bf16 v[96:99], v[174:177], v[190:193], v[96:99]
	v_mfma_f32_16x16x32_bf16 v[84:87], v[166:169], v[198:201], v[84:87]
	v_mfma_f32_16x16x32_bf16 v[80:83], v[174:177], v[198:201], v[80:83]
	v_mfma_f32_16x16x32_bf16 v[68:71], v[166:169], v[232:235], v[68:71]
	v_mfma_f32_16x16x32_bf16 v[64:67], v[174:177], v[232:235], v[64:67]
	s_barrier
; #define PG8_STAGE(bufoff, gbase, voff) do { _Pragma("unroll") for (int _i = 0; _i < 2; ++_i) \
;         __builtin_amdgcn_global_load_lds((const unsigned*)((const char*)(gbase) + (voff)[_i]), (PG8_LAS unsigned*)(lds + (bufoff) + ldsw + _i * 8192), 16, 0, 0); } while (0)
; #define PG8_LDA(dst, b, h) do { _Pragma("unroll") for (int m = 0; m < 4; ++m) _Pragma("unroll") for (int k = 0; k < 2; ++k) dst[m][k] = *(const PG8_LAS bf16x8*)(lds + PG8_SA(b, h) + aoff + m * 2048 + k * 1024); } while (0)
; #define PG8_MMA(ai, bj, At, Bt) do { __builtin_amdgcn_s_setprio(1); _Pragma("unroll") for (int m = 0; m < 4; ++m) _Pragma("unroll") for (int n = 0; n < 2; ++n) _Pragma("unroll") for (int k = 0; k < 2; ++k) \
;         acc[ai][bj][m][n] = __builtin_amdgcn_mfma_f32_16x16x32_bf16(Bt[n][k], At[m][k], acc[ai][bj][m][n], 0, 0, 0); __builtin_amdgcn_s_setprio(0); } while (0)
; #define PG8_WAIT_V(n) asm volatile("s_waitcnt vmcnt(" #n ")" ::: "memory")
; #define PG8_WAIT_L(n) asm volatile("s_waitcnt lgkmcnt(" #n ")" ::: "memory")
; #define PG8_BAR __builtin_amdgcn_s_barrier()
; #define PG8_SCHED __builtin_amdgcn_sched_barrier(0)
; template <class Epi, class Sched, bool ALIGN_EPI = false, bool SP2 = false>
; __device__ __forceinline__ void gemm_phase(PG8_LAS unsigned char* lds, const Gemm g, const Sched& S, const Epi& E) {
;     ...
;             PG8_LDA(At, 0, 1); PG8_STAGE(PG8_SB(0, 0), b2, voffB); PG8_STAGE(PG8_SB(0, 1), b2 + hstep, voffB);
;             PG8_WAIT_V(6); PG8_WAIT_L(0); PG8_BAR; PG8_MMA(1, 0, At, B0); PG8_MMA(1, 1, At, B1); PG8_BAR; PG8_SCHED;
	s_add_i32 s53, s53, s23
	v_lshl_add_u64 v[202:203], s[16:17], 0, v[204:205]
	s_mov_b32 m0, s53
	ds_read_b128 v[178:181], v149 offset:16384
	ds_read_b128 v[182:185], v149 offset:17408
	ds_read_b128 v[186:189], v149 offset:18432
	ds_read_b128 v[190:193], v149 offset:19456
	ds_read_b128 v[194:197], v149 offset:20480
	ds_read_b128 v[198:201], v149 offset:21504
	ds_read_b128 v[218:221], v149 offset:22528
	ds_read_b128 v[232:235], v149 offset:23552
	global_load_lds_dwordx4 v[202:203], off
	s_add_i32 m0, s53, 0x2000
	s_add_u32 s78, s16, 0x80000
	v_lshl_add_u64 v[206:207], s[16:17], 0, v[128:129]
	s_addc_u32 s79, s17, 0
	s_add_i32 s53, s92, s23
	global_load_lds_dwordx4 v[206:207], off
	v_lshl_add_u64 v[208:209], s[78:79], 0, v[204:205]
	s_mov_b32 m0, s53
	s_nop 0
	global_load_lds_dwordx4 v[208:209], off
	v_lshl_add_u64 v[208:209], s[78:79], 0, v[128:129]
	s_add_i32 m0, s53, 0x2000
	s_nop 0
	global_load_lds_dwordx4 v[208:209], off
	s_waitcnt vmcnt(6)
	s_waitcnt lgkmcnt(0)
	s_barrier
	v_mfma_f32_16x16x32_bf16 v[60:63], v[142:145], v[178:181], 0
	v_mfma_f32_16x16x32_bf16 v[56:59], v[154:157], v[178:181], 0
	v_mfma_f32_16x16x32_bf16 v[44:47], v[142:145], v[186:189], 0
	v_mfma_f32_16x16x32_bf16 v[40:43], v[154:157], v[186:189], 0
	v_mfma_f32_16x16x32_bf16 v[28:31], v[142:145], v[194:197], 0
	v_mfma_f32_16x16x32_bf16 v[24:27], v[154:157], v[194:197], 0
	v_mfma_f32_16x16x32_bf16 v[12:15], v[142:145], v[218:221], 0
	v_mfma_f32_16x16x32_bf16 v[8:11], v[154:157], v[218:221], 0
	v_mfma_f32_16x16x32_bf16 v[60:63], v[150:153], v[182:185], v[60:63]
	v_mfma_f32_16x16x32_bf16 v[56:59], v[158:161], v[182:185], v[56:59]
	v_mfma_f32_16x16x32_bf16 v[44:47], v[150:153], v[190:193], v[44:47]
	v_mfma_f32_16x16x32_bf16 v[40:43], v[158:161], v[190:193], v[40:43]
	v_mfma_f32_16x16x32_bf16 v[28:31], v[150:153], v[198:201], v[28:31]
	v_mfma_f32_16x16x32_bf16 v[24:27], v[158:161], v[198:201], v[24:27]
	v_mfma_f32_16x16x32_bf16 v[12:15], v[150:153], v[232:235], v[12:15]
	v_mfma_f32_16x16x32_bf16 v[8:11], v[158:161], v[232:235], v[8:11]
	v_mfma_f32_16x16x32_bf16 v[52:55], v[162:165], v[178:181], 0
	v_mfma_f32_16x16x32_bf16 v[48:51], v[170:173], v[178:181], 0
	v_mfma_f32_16x16x32_bf16 v[36:39], v[162:165], v[186:189], 0
	v_mfma_f32_16x16x32_bf16 v[32:35], v[170:173], v[186:189], 0
	v_mfma_f32_16x16x32_bf16 v[20:23], v[162:165], v[194:197], 0
	v_mfma_f32_16x16x32_bf16 v[16:19], v[170:173], v[194:197], 0
	v_mfma_f32_16x16x32_bf16 v[4:7], v[162:165], v[218:221], 0
	v_mfma_f32_16x16x32_bf16 v[0:3], v[170:173], v[218:221], 0
	v_mfma_f32_16x16x32_bf16 v[52:55], v[166:169], v[182:185], v[52:55]
	v_mfma_f32_16x16x32_bf16 v[48:51], v[174:177], v[182:185], v[48:51]
	v_mfma_f32_16x16x32_bf16 v[36:39], v[166:169], v[190:193], v[36:39]
	v_mfma_f32_16x16x32_bf16 v[32:35], v[174:177], v[190:193], v[32:35]
	v_mfma_f32_16x16x32_bf16 v[20:23], v[166:169], v[198:201], v[20:23]
	v_mfma_f32_16x16x32_bf16 v[16:19], v[174:177], v[198:201], v[16:19]
	v_mfma_f32_16x16x32_bf16 v[4:7], v[166:169], v[232:235], v[4:7]
	v_mfma_f32_16x16x32_bf16 v[0:3], v[174:177], v[232:235], v[0:3]
	s_barrier
	s_branch .Lpl_qk

; #define PG8_STAGE(bufoff, gbase, voff) do { _Pragma("unroll") for (int _i = 0; _i < 2; ++_i) \
;         __builtin_amdgcn_global_load_lds((const unsigned*)((const char*)(gbase) + (voff)[_i]), (PG8_LAS unsigned*)(lds + (bufoff) + ldsw + _i * 8192), 16, 0, 0); } while (0)
; #define PG8_LDA(dst, b, h) do { _Pragma("unroll") for (int m = 0; m < 4; ++m) _Pragma("unroll") for (int k = 0; k < 2; ++k) dst[m][k] = *(const PG8_LAS bf16x8*)(lds + PG8_SA(b, h) + aoff + m * 2048 + k * 1024); } while (0)
; #define PG8_LDB(dst, b, h) do { _Pragma("unroll") for (int n = 0; n < 2; ++n) _Pragma("unroll") for (int k = 0; k < 2; ++k) dst[n][k] = *(const PG8_LAS bf16x8*)(lds + PG8_SB(b, h) + boff + n * 2048 + k * 1024); } while (0)
; #define PG8_MMA(ai, bj, At, Bt) do { __builtin_amdgcn_s_setprio(1); _Pragma("unroll") for (int m = 0; m < 4; ++m) _Pragma("unroll") for (int n = 0; n < 2; ++n) _Pragma("unroll") for (int k = 0; k < 2; ++k) \
;         acc[ai][bj][m][n] = __builtin_amdgcn_mfma_f32_16x16x32_bf16(Bt[n][k], At[m][k], acc[ai][bj][m][n], 0, 0, 0); __builtin_amdgcn_s_setprio(0); } while (0)
; #define PG8_WAIT_V(n) asm volatile("s_waitcnt vmcnt(" #n ")" ::: "memory")
; #define PG8_WAIT_L(n) asm volatile("s_waitcnt lgkmcnt(" #n ")" ::: "memory")
; #define PG8_BAR __builtin_amdgcn_s_barrier()
; #define PG8_SCHED __builtin_amdgcn_sched_barrier(0)
; template <class Epi, class Sched, bool ALIGN_EPI = false, bool SP2 = false>
; __device__ __forceinline__ void gemm_phase(PG8_LAS unsigned char* lds, const Gemm g, const Sched& S, const Epi& E) {
;     ...
;             PG8_LDB(B0, 1, 0); PG8_LDB(B1, 1, 1); PG8_SCHED; PG8_LDA(At, 1, 0); PG8_STAGE(PG8_SA(0, 0), a2, voffA); PG8_STAGE(PG8_SA(0, 1), a2 + hstep, voffA);
;             PG8_WAIT_V(8); PG8_WAIT_L(0); PG8_BAR; PG8_MMA(0, 0, At, B0); PG8_MMA(0, 1, At, B1); PG8_BAR; PG8_SCHED;
;             PG8_LDA(At, 1, 1); PG8_STAGE(PG8_SB(1, 0), b3, voffB); PG8_STAGE(PG8_SB(1, 1), b3 + hstep, voffB); (void)a3;
;             PG8_WAIT_V(6); PG8_WAIT_L(0); PG8_BAR; PG8_MMA(1, 0, At, B0); PG8_MMA(1, 1, At, B1); PG8_BAR; PG8_SCHED;
.Lpl_qk:
	s_add_i32 s53, 0, 0x18000
	s_add_i32 s78, 0, 0x1c000
	v_add_u32_e32 v158, s53, v147
	v_add_u32_e32 v174, s78, v147
	ds_read_b128 v[142:145], v158
	ds_read_b128 v[150:153], v158 offset:1024
	ds_read_b128 v[154:157], v158 offset:2048
	ds_read_b128 v[158:161], v158 offset:3072
	ds_read_b128 v[162:165], v174
	ds_read_b128 v[166:169], v174 offset:1024
	ds_read_b128 v[170:173], v174 offset:2048
	ds_read_b128 v[174:177], v174 offset:3072
	s_mov_b32 m0, s97
	v_lshl_add_u64 v[208:209], s[44:45], 0, v[132:133]
	ds_read_b128 v[178:181], v149 offset:32768
	ds_read_b128 v[182:185], v149 offset:33792
	ds_read_b128 v[186:189], v149 offset:34816
	ds_read_b128 v[190:193], v149 offset:35840
	ds_read_b128 v[194:197], v149 offset:36864
	ds_read_b128 v[198:201], v149 offset:37888
	ds_read_b128 v[218:221], v149 offset:38912
	ds_read_b128 v[232:235], v149 offset:39936
	global_load_lds_dwordx4 v[208:209], off
	v_lshl_add_u64 v[208:209], s[44:45], 0, v[130:131]
	s_add_u32 s44, s44, 0x80000
	s_mov_b32 m0, s20
	s_addc_u32 s45, s45, 0
	global_load_lds_dwordx4 v[208:209], off
	v_lshl_add_u64 v[208:209], s[44:45], 0, v[132:133]
	s_mov_b32 m0, s21
	s_nop 0
	global_load_lds_dwordx4 v[208:209], off
	v_lshl_add_u64 v[208:209], s[44:45], 0, v[130:131]
	s_mov_b32 m0, s57
	s_nop 0
	global_load_lds_dwordx4 v[208:209], off
	s_waitcnt vmcnt(8)
	s_waitcnt lgkmcnt(0)
	s_barrier
	v_mfma_f32_16x16x32_bf16 v[124:127], v[142:145], v[178:181], v[124:127]
	v_mfma_f32_16x16x32_bf16 v[120:123], v[154:157], v[178:181], v[120:123]
	v_mfma_f32_16x16x32_bf16 v[108:111], v[142:145], v[186:189], v[108:111]
	v_mfma_f32_16x16x32_bf16 v[104:107], v[154:157], v[186:189], v[104:107]
	v_mfma_f32_16x16x32_bf16 v[92:95], v[142:145], v[194:197], v[92:95]
	v_mfma_f32_16x16x32_bf16 v[88:91], v[154:157], v[194:197], v[88:91]
	v_mfma_f32_16x16x32_bf16 v[76:79], v[142:145], v[218:221], v[76:79]
	v_mfma_f32_16x16x32_bf16 v[72:75], v[154:157], v[218:221], v[72:75]
	v_mfma_f32_16x16x32_bf16 v[124:127], v[150:153], v[182:185], v[124:127]
	v_mfma_f32_16x16x32_bf16 v[120:123], v[158:161], v[182:185], v[120:123]
	v_mfma_f32_16x16x32_bf16 v[108:111], v[150:153], v[190:193], v[108:111]
	v_mfma_f32_16x16x32_bf16 v[104:107], v[158:161], v[190:193], v[104:107]
	v_mfma_f32_16x16x32_bf16 v[92:95], v[150:153], v[198:201], v[92:95]
	v_mfma_f32_16x16x32_bf16 v[88:91], v[158:161], v[198:201], v[88:91]
	v_mfma_f32_16x16x32_bf16 v[76:79], v[150:153], v[232:235], v[76:79]
	v_mfma_f32_16x16x32_bf16 v[72:75], v[158:161], v[232:235], v[72:75]
	v_mfma_f32_16x16x32_bf16 v[116:119], v[162:165], v[178:181], v[116:119]
	v_mfma_f32_16x16x32_bf16 v[112:115], v[170:173], v[178:181], v[112:115]
	v_mfma_f32_16x16x32_bf16 v[100:103], v[162:165], v[186:189], v[100:103]
	v_mfma_f32_16x16x32_bf16 v[96:99], v[170:173], v[186:189], v[96:99]
	v_mfma_f32_16x16x32_bf16 v[84:87], v[162:165], v[194:197], v[84:87]
	v_mfma_f32_16x16x32_bf16 v[80:83], v[170:173], v[194:197], v[80:83]
	v_mfma_f32_16x16x32_bf16 v[68:71], v[162:165], v[218:221], v[68:71]
	v_mfma_f32_16x16x32_bf16 v[64:67], v[170:173], v[218:221], v[64:67]
	v_mfma_f32_16x16x32_bf16 v[116:119], v[166:169], v[182:185], v[116:119]
	v_mfma_f32_16x16x32_bf16 v[112:115], v[174:177], v[182:185], v[112:115]
	v_mfma_f32_16x16x32_bf16 v[100:103], v[166:169], v[190:193], v[100:103]
	v_mfma_f32_16x16x32_bf16 v[96:99], v[174:177], v[190:193], v[96:99]
	v_mfma_f32_16x16x32_bf16 v[84:87], v[166:169], v[198:201], v[84:87]
	v_mfma_f32_16x16x32_bf16 v[80:83], v[174:177], v[198:201], v[80:83]
	v_mfma_f32_16x16x32_bf16 v[68:71], v[166:169], v[232:235], v[68:71]
	v_mfma_f32_16x16x32_bf16 v[64:67], v[174:177], v[232:235], v[64:67]
	s_barrier
	s_add_i32 s44, s53, s23
	v_lshl_add_u64 v[202:203], v[202:203], 0, s[26:27]
	s_mov_b32 m0, s44
	ds_read_b128 v[178:181], v149 offset:49152
	ds_read_b128 v[182:185], v149 offset:50176
	ds_read_b128 v[186:189], v149 offset:51200
	ds_read_b128 v[190:193], v149 offset:52224
	ds_read_b128 v[194:197], v149 offset:53248
	ds_read_b128 v[198:201], v149 offset:54272
	ds_read_b128 v[218:221], v149 offset:55296
	ds_read_b128 v[232:235], v149 offset:56320
	global_load_lds_dwordx4 v[202:203], off
	s_add_i32 m0, s44, 0x2000
	s_add_u32 s16, s16, 0x80080
	v_lshl_add_u64 v[202:203], v[206:207], 0, s[26:27]
	s_addc_u32 s17, s17, 0
	s_add_i32 s44, s78, s23
	global_load_lds_dwordx4 v[202:203], off
	v_lshl_add_u64 v[202:203], s[16:17], 0, v[204:205]
	s_mov_b32 m0, s44
	s_nop 0
	global_load_lds_dwordx4 v[202:203], off
	v_lshl_add_u64 v[202:203], s[16:17], 0, v[128:129]
	s_add_i32 m0, s44, 0x2000
	s_nop 0
	global_load_lds_dwordx4 v[202:203], off
	s_waitcnt vmcnt(6)
	s_waitcnt lgkmcnt(0)
	s_barrier
	v_mfma_f32_16x16x32_bf16 v[60:63], v[142:145], v[178:181], v[60:63]
	v_mfma_f32_16x16x32_bf16 v[56:59], v[154:157], v[178:181], v[56:59]
	v_mfma_f32_16x16x32_bf16 v[44:47], v[142:145], v[186:189], v[44:47]
	v_mfma_f32_16x16x32_bf16 v[40:43], v[154:157], v[186:189], v[40:43]
	v_mfma_f32_16x16x32_bf16 v[28:31], v[142:145], v[194:197], v[28:31]
	v_mfma_f32_16x16x32_bf16 v[24:27], v[154:157], v[194:197], v[24:27]
	v_mfma_f32_16x16x32_bf16 v[12:15], v[142:145], v[218:221], v[12:15]
	v_mfma_f32_16x16x32_bf16 v[8:11], v[154:157], v[218:221], v[8:11]
	v_mfma_f32_16x16x32_bf16 v[60:63], v[150:153], v[182:185], v[60:63]
	v_mfma_f32_16x16x32_bf16 v[56:59], v[158:161], v[182:185], v[56:59]
	v_mfma_f32_16x16x32_bf16 v[44:47], v[150:153], v[190:193], v[44:47]
	v_mfma_f32_16x16x32_bf16 v[40:43], v[158:161], v[190:193], v[40:43]
	v_mfma_f32_16x16x32_bf16 v[28:31], v[150:153], v[198:201], v[28:31]
	v_mfma_f32_16x16x32_bf16 v[24:27], v[158:161], v[198:201], v[24:27]
	v_mfma_f32_16x16x32_bf16 v[12:15], v[150:153], v[232:235], v[12:15]
	v_mfma_f32_16x16x32_bf16 v[8:11], v[158:161], v[232:235], v[8:11]
	v_mfma_f32_16x16x32_bf16 v[52:55], v[162:165], v[178:181], v[52:55]
	v_mfma_f32_16x16x32_bf16 v[48:51], v[170:173], v[178:181], v[48:51]
	v_mfma_f32_16x16x32_bf16 v[36:39], v[162:165], v[186:189], v[36:39]
	v_mfma_f32_16x16x32_bf16 v[32:35], v[170:173], v[186:189], v[32:35]
	v_mfma_f32_16x16x32_bf16 v[20:23], v[162:165], v[194:197], v[20:23]
	v_mfma_f32_16x16x32_bf16 v[16:19], v[170:173], v[194:197], v[16:19]
	v_mfma_f32_16x16x32_bf16 v[4:7], v[162:165], v[218:221], v[4:7]
	v_mfma_f32_16x16x32_bf16 v[0:3], v[170:173], v[218:221], v[0:3]
	v_mfma_f32_16x16x32_bf16 v[52:55], v[166:169], v[182:185], v[52:55]
	v_mfma_f32_16x16x32_bf16 v[48:51], v[174:177], v[182:185], v[48:51]
	v_mfma_f32_16x16x32_bf16 v[36:39], v[166:169], v[190:193], v[36:39]
	v_mfma_f32_16x16x32_bf16 v[32:35], v[174:177], v[190:193], v[32:35]
	v_mfma_f32_16x16x32_bf16 v[20:23], v[166:169], v[198:201], v[20:23]
	v_mfma_f32_16x16x32_bf16 v[16:19], v[174:177], v[198:201], v[16:19]
	v_mfma_f32_16x16x32_bf16 v[4:7], v[166:169], v[232:235], v[4:7]
	v_mfma_f32_16x16x32_bf16 v[0:3], v[174:177], v[232:235], v[0:3]
	s_barrier
	s_add_i32 s52, s52, 2
	s_add_u32 s10, s10, 0x100
	s_addc_u32 s11, s11, 0
	s_cmp_gt_u32 s52, 29
	s_cbranch_scc0 .LBB0_212
	s_and_b64 vcc, exec, s[76:77]
	s_cbranch_vccz .LBB0_215
	s_barrier

; #define PG8_STAGE(bufoff, gbase, voff) do { _Pragma("unroll") for (int _i = 0; _i < 2; ++_i) \
;         __builtin_amdgcn_global_load_lds((const unsigned*)((const char*)(gbase) + (voff)[_i]), (PG8_LAS unsigned*)(lds + (bufoff) + ldsw + _i * 8192), 16, 0, 0); } while (0)
; #define PG8_LDA(dst, b, h) do { _Pragma("unroll") for (int m = 0; m < 4; ++m) _Pragma("unroll") for (int k = 0; k < 2; ++k) dst[m][k] = *(const PG8_LAS bf16x8*)(lds + PG8_SA(b, h) + aoff + m * 2048 + k * 1024); } while (0)
; #define PG8_LDB(dst, b, h) do { _Pragma("unroll") for (int n = 0; n < 2; ++n) _Pragma("unroll") for (int k = 0; k < 2; ++k) dst[n][k] = *(const PG8_LAS bf16x8*)(lds + PG8_SB(b, h) + boff + n * 2048 + k * 1024); } while (0)
; #define PG8_MMA(ai, bj, At, Bt) do { __builtin_amdgcn_s_setprio(1); _Pragma("unroll") for (int m = 0; m < 4; ++m) _Pragma("unroll") for (int n = 0; n < 2; ++n) _Pragma("unroll") for (int k = 0; k < 2; ++k) \
;         acc[ai][bj][m][n] = __builtin_amdgcn_mfma_f32_16x16x32_bf16(Bt[n][k], At[m][k], acc[ai][bj][m][n], 0, 0, 0); __builtin_amdgcn_s_setprio(0); } while (0)
; #define PG8_WAIT_V(n) asm volatile("s_waitcnt vmcnt(" #n ")" ::: "memory")
; #define PG8_WAIT_L(n) asm volatile("s_waitcnt lgkmcnt(" #n ")" ::: "memory")
; template <class Epi, class Sched, bool ALIGN_EPI = false, bool SP2 = false>
; __device__ __forceinline__ void gemm_phase(PG8_LAS unsigned char* lds, const Gemm g, const Sched& S, const Epi& E) {
;     ...
;         const bool has_next = S.next(ui + 1, nxt);
;         const char* nA = has_next ? (const char*)g.A + (size_t)nxt.pm * tstep : cA; const char* nB = has_next ? (const char*)g.Bt + (size_t)nxt.pn * tstep : cB;
;         for (int t = 0; t < nt; t += 2) {
;             const bool last = (t == nt - 2);
;             const char* a1 = cA + (size_t)(t + 1) * kstep;
;             const char* a2 = last ? nA : cA + (size_t)(t + 2) * kstep; const char* b2 = last ? nB : cB + (size_t)(t + 2) * kstep;
;             const char* a3 = a2 + kstep; const char* b3 = b2 + kstep;
;             if (last && has_next) S.a_ready(nxt);
;             if constexpr (SP2) {
;             PG8_LDB(B0, 0, 0); PG8_LDB(B1, 0, 1); PG8_SCHED; PG8_LDA(At, 0, 0); PG8_STAGE(PG8_SA(1, 0), a1, voffA); PG8_STAGE(PG8_SA(1, 1), a1 + hstep, voffA);
;             PG8_WAIT_V(8); PG8_WAIT_L(0); PG8_BAR; PG8_MMA(0, 0, At, B0); PG8_MMA(0, 1, At, B1); PG8_BAR; PG8_SCHED;
.LBB0_231:
	s_ashr_i32 s47, s46, 31
	s_lshl_b64 s[52:53], s[46:47], 20
	s_add_u32 s72, s20, s52
	s_addc_u32 s73, s21, s53
	s_and_b64 s[52:53], s[38:39], exec
	s_cselect_b32 s47, s73, s17
	s_cselect_b32 s68, s72, s16
	s_ashr_i32 s11, s10, 31
	s_lshl_b64 s[52:53], s[10:11], 20
	s_add_u32 s76, s22, s52
	s_addc_u32 s77, s75, s53
	s_and_b64 s[52:53], s[38:39], exec
	s_cselect_b32 s11, s77, s45
	s_cselect_b32 s69, s76, s44
	s_add_u32 s70, s44, 0x100
	s_addc_u32 s71, s45, 0
	v_lshl_add_u64 v[96:97], s[16:17], 0, v[150:151]
	v_lshl_add_u64 v[98:99], s[16:17], 0, v[152:153]
	s_mov_b32 s52, -2
	s_mov_b64 s[88:89], 0
	s_add_u32 s44, s16, s88
	s_addc_u32 s45, s17, s89
	s_add_u32 s53, s44, 0x100
	s_addc_u32 s78, s45, 0
	s_add_u32 s44, s70, s88
	s_addc_u32 s45, s71, s89
	s_add_i32 s79, 0, 0x10000
	s_cmpk_eq_i32 s88, 0xf00
	s_cselect_b32 s45, s11, s45
	s_cselect_b32 s44, s69, s44
	s_cselect_b32 s95, s47, s78
	s_cselect_b32 s94, s68, s53
	s_add_i32 s53, 0, 0x14000
	v_add_u32_e32 v154, s79, v161
	v_add_u32_e32 v158, s53, v161
	ds_read_b128 v[100:103], v154
	ds_read_b128 v[104:107], v154 offset:1024
	ds_read_b128 v[108:111], v154 offset:2048
	ds_read_b128 v[154:157], v154 offset:3072
	ds_read_b128 v[164:167], v158
	ds_read_b128 v[168:171], v158 offset:1024
	ds_read_b128 v[172:175], v158 offset:2048
	ds_read_b128 v[176:179], v158 offset:3072
	v_lshl_add_u64 v[158:159], v[96:97], 0, s[88:89]
	v_lshl_add_u64 v[206:207], v[158:159], 0, s[26:27]
	s_add_i32 m0, s57, 0x8000
	ds_read_b128 v[180:183], v163
	ds_read_b128 v[184:187], v163 offset:1024
	ds_read_b128 v[188:191], v163 offset:2048
	ds_read_b128 v[192:195], v163 offset:3072
	ds_read_b128 v[196:199], v163 offset:4096
	ds_read_b128 v[200:203], v163 offset:5120
	ds_read_b128 v[218:221], v163 offset:6144
	ds_read_b128 v[232:235], v163 offset:7168
	global_load_lds_dwordx4 v[206:207], off
	v_lshl_add_u64 v[206:207], v[98:99], 0, s[88:89]
	v_lshl_add_u64 v[208:209], v[206:207], 0, s[26:27]
	s_add_i32 m0, s57, 0xa000
	v_lshl_add_u64 v[158:159], v[158:159], 0, s[28:29]
	global_load_lds_dwordx4 v[208:209], off
	s_add_i32 m0, s57, 0xc000
	s_nop 0
	global_load_lds_dwordx4 v[158:159], off
	v_lshl_add_u64 v[158:159], v[206:207], 0, s[28:29]
	s_add_i32 m0, s57, 0xe000
	s_nop 0
	global_load_lds_dwordx4 v[158:159], off
	s_waitcnt vmcnt(8)
	s_waitcnt lgkmcnt(0)
	s_barrier
	v_mfma_f32_16x16x32_bf16 v[140:143], v[100:103], v[180:183], 0
	v_mfma_f32_16x16x32_bf16 v[136:139], v[108:111], v[180:183], 0
	v_mfma_f32_16x16x32_bf16 v[124:127], v[100:103], v[188:191], 0
	v_mfma_f32_16x16x32_bf16 v[120:123], v[108:111], v[188:191], 0
	v_mfma_f32_16x16x32_bf16 v[92:95], v[100:103], v[196:199], 0
	v_mfma_f32_16x16x32_bf16 v[88:91], v[108:111], v[196:199], 0
	v_mfma_f32_16x16x32_bf16 v[76:79], v[100:103], v[218:221], 0
	v_mfma_f32_16x16x32_bf16 v[72:75], v[108:111], v[218:221], 0
	v_mfma_f32_16x16x32_bf16 v[140:143], v[104:107], v[184:187], v[140:143]
	v_mfma_f32_16x16x32_bf16 v[136:139], v[154:157], v[184:187], v[136:139]
	v_mfma_f32_16x16x32_bf16 v[124:127], v[104:107], v[192:195], v[124:127]
	v_mfma_f32_16x16x32_bf16 v[120:123], v[154:157], v[192:195], v[120:123]
	v_mfma_f32_16x16x32_bf16 v[92:95], v[104:107], v[200:203], v[92:95]
	v_mfma_f32_16x16x32_bf16 v[88:91], v[154:157], v[200:203], v[88:91]
	v_mfma_f32_16x16x32_bf16 v[76:79], v[104:107], v[232:235], v[76:79]
	v_mfma_f32_16x16x32_bf16 v[72:75], v[154:157], v[232:235], v[72:75]
	v_mfma_f32_16x16x32_bf16 v[132:135], v[164:167], v[180:183], 0
	v_mfma_f32_16x16x32_bf16 v[128:131], v[172:175], v[180:183], 0
	v_mfma_f32_16x16x32_bf16 v[116:119], v[164:167], v[188:191], 0
	v_mfma_f32_16x16x32_bf16 v[112:115], v[172:175], v[188:191], 0
	v_mfma_f32_16x16x32_bf16 v[84:87], v[164:167], v[196:199], 0
	v_mfma_f32_16x16x32_bf16 v[80:83], v[172:175], v[196:199], 0
	v_mfma_f32_16x16x32_bf16 v[68:71], v[164:167], v[218:221], 0
	v_mfma_f32_16x16x32_bf16 v[64:67], v[172:175], v[218:221], 0
	v_mfma_f32_16x16x32_bf16 v[132:135], v[168:171], v[184:187], v[132:135]
	v_mfma_f32_16x16x32_bf16 v[128:131], v[176:179], v[184:187], v[128:131]
	v_mfma_f32_16x16x32_bf16 v[116:119], v[168:171], v[192:195], v[116:119]
	v_mfma_f32_16x16x32_bf16 v[112:115], v[176:179], v[192:195], v[112:115]
	v_mfma_f32_16x16x32_bf16 v[84:87], v[168:171], v[200:203], v[84:87]
	v_mfma_f32_16x16x32_bf16 v[80:83], v[176:179], v[200:203], v[80:83]
	v_mfma_f32_16x16x32_bf16 v[68:71], v[168:171], v[232:235], v[68:71]
	v_mfma_f32_16x16x32_bf16 v[64:67], v[176:179], v[232:235], v[64:67]
	s_barrier
; #define PG8_STAGE(bufoff, gbase, voff) do { _Pragma("unroll") for (int _i = 0; _i < 2; ++_i) \
;         __builtin_amdgcn_global_load_lds((const unsigned*)((const char*)(gbase) + (voff)[_i]), (PG8_LAS unsigned*)(lds + (bufoff) + ldsw + _i * 8192), 16, 0, 0); } while (0)
; #define PG8_LDA(dst, b, h) do { _Pragma("unroll") for (int m = 0; m < 4; ++m) _Pragma("unroll") for (int k = 0; k < 2; ++k) dst[m][k] = *(const PG8_LAS bf16x8*)(lds + PG8_SA(b, h) + aoff + m * 2048 + k * 1024); } while (0)
; #define PG8_MMA(ai, bj, At, Bt) do { __builtin_amdgcn_s_setprio(1); _Pragma("unroll") for (int m = 0; m < 4; ++m) _Pragma("unroll") for (int n = 0; n < 2; ++n) _Pragma("unroll") for (int k = 0; k < 2; ++k) \
;         acc[ai][bj][m][n] = __builtin_amdgcn_mfma_f32_16x16x32_bf16(Bt[n][k], At[m][k], acc[ai][bj][m][n], 0, 0, 0); __builtin_amdgcn_s_setprio(0); } while (0)
; #define PG8_WAIT_V(n) asm volatile("s_waitcnt vmcnt(" #n ")" ::: "memory")
; #define PG8_WAIT_L(n) asm volatile("s_waitcnt lgkmcnt(" #n ")" ::: "memory")
; #define PG8_BAR __builtin_amdgcn_s_barrier()
; #define PG8_SCHED __builtin_amdgcn_sched_barrier(0)
; template <class Epi, class Sched, bool ALIGN_EPI = false, bool SP2 = false>
; __device__ __forceinline__ void gemm_phase(PG8_LAS unsigned char* lds, const Gemm g, const Sched& S, const Epi& E) {
;     ...
;             PG8_LDA(At, 0, 1); PG8_STAGE(PG8_SB(0, 0), b2, voffB); PG8_STAGE(PG8_SB(0, 1), b2 + hstep, voffB);
;             PG8_WAIT_V(6); PG8_WAIT_L(0); PG8_BAR; PG8_MMA(1, 0, At, B0); PG8_MMA(1, 1, At, B1); PG8_BAR; PG8_SCHED;
	s_add_i32 s78, s79, s23
	v_lshl_add_u64 v[158:159], s[44:45], 0, v[204:205]
	s_mov_b32 m0, s78
	ds_read_b128 v[180:183], v163 offset:16384
	ds_read_b128 v[184:187], v163 offset:17408
	ds_read_b128 v[188:191], v163 offset:18432
	ds_read_b128 v[192:195], v163 offset:19456
	ds_read_b128 v[196:199], v163 offset:20480
	ds_read_b128 v[200:203], v163 offset:21504
	ds_read_b128 v[218:221], v163 offset:22528
	ds_read_b128 v[232:235], v163 offset:23552
	global_load_lds_dwordx4 v[158:159], off
	s_add_i32 m0, s78, 0x2000
	s_add_u32 s78, s44, 0x80000
	v_lshl_add_u64 v[206:207], s[44:45], 0, v[144:145]
	s_addc_u32 s79, s45, 0
	s_add_i32 s53, s53, s23
	global_load_lds_dwordx4 v[206:207], off
	v_lshl_add_u64 v[208:209], s[78:79], 0, v[204:205]
	s_mov_b32 m0, s53
	s_nop 0
	global_load_lds_dwordx4 v[208:209], off
	v_lshl_add_u64 v[208:209], s[78:79], 0, v[144:145]
	s_add_i32 m0, s53, 0x2000
	s_nop 0
	global_load_lds_dwordx4 v[208:209], off
	s_waitcnt vmcnt(6)
	s_waitcnt lgkmcnt(0)
	s_barrier
	v_mfma_f32_16x16x32_bf16 v[60:63], v[100:103], v[180:183], 0
	v_mfma_f32_16x16x32_bf16 v[56:59], v[108:111], v[180:183], 0
	v_mfma_f32_16x16x32_bf16 v[48:51], v[100:103], v[188:191], 0
	v_mfma_f32_16x16x32_bf16 v[40:43], v[108:111], v[188:191], 0
	v_mfma_f32_16x16x32_bf16 v[32:35], v[100:103], v[196:199], 0
	v_mfma_f32_16x16x32_bf16 v[24:27], v[108:111], v[196:199], 0
	v_mfma_f32_16x16x32_bf16 v[16:19], v[100:103], v[218:221], 0
	v_mfma_f32_16x16x32_bf16 v[8:11], v[108:111], v[218:221], 0
	v_mfma_f32_16x16x32_bf16 v[60:63], v[104:107], v[184:187], v[60:63]
	v_mfma_f32_16x16x32_bf16 v[56:59], v[154:157], v[184:187], v[56:59]
	v_mfma_f32_16x16x32_bf16 v[48:51], v[104:107], v[192:195], v[48:51]
	v_mfma_f32_16x16x32_bf16 v[40:43], v[154:157], v[192:195], v[40:43]
	v_mfma_f32_16x16x32_bf16 v[32:35], v[104:107], v[200:203], v[32:35]
	v_mfma_f32_16x16x32_bf16 v[24:27], v[154:157], v[200:203], v[24:27]
	v_mfma_f32_16x16x32_bf16 v[16:19], v[104:107], v[232:235], v[16:19]
	v_mfma_f32_16x16x32_bf16 v[8:11], v[154:157], v[232:235], v[8:11]
	v_mfma_f32_16x16x32_bf16 v[52:55], v[164:167], v[180:183], 0
	v_mfma_f32_16x16x32_bf16 v[44:47], v[172:175], v[180:183], 0
	v_mfma_f32_16x16x32_bf16 v[36:39], v[164:167], v[188:191], 0
	v_mfma_f32_16x16x32_bf16 v[28:31], v[172:175], v[188:191], 0
	v_mfma_f32_16x16x32_bf16 v[20:23], v[164:167], v[196:199], 0
	v_mfma_f32_16x16x32_bf16 v[12:15], v[172:175], v[196:199], 0
	v_mfma_f32_16x16x32_bf16 v[4:7], v[164:167], v[218:221], 0
	v_mfma_f32_16x16x32_bf16 v[0:3], v[172:175], v[218:221], 0
	v_mfma_f32_16x16x32_bf16 v[52:55], v[168:171], v[184:187], v[52:55]
	v_mfma_f32_16x16x32_bf16 v[44:47], v[176:179], v[184:187], v[44:47]
	v_mfma_f32_16x16x32_bf16 v[36:39], v[168:171], v[192:195], v[36:39]
	v_mfma_f32_16x16x32_bf16 v[28:31], v[176:179], v[192:195], v[28:31]
	v_mfma_f32_16x16x32_bf16 v[20:23], v[168:171], v[200:203], v[20:23]
	v_mfma_f32_16x16x32_bf16 v[12:15], v[176:179], v[200:203], v[12:15]
	v_mfma_f32_16x16x32_bf16 v[4:7], v[168:171], v[232:235], v[4:7]
	v_mfma_f32_16x16x32_bf16 v[0:3], v[176:179], v[232:235], v[0:3]
	s_barrier
	s_branch .Lpl_vt

; #define PG8_STAGE(bufoff, gbase, voff) do { _Pragma("unroll") for (int _i = 0; _i < 2; ++_i) \
;         __builtin_amdgcn_global_load_lds((const unsigned*)((const char*)(gbase) + (voff)[_i]), (PG8_LAS unsigned*)(lds + (bufoff) + ldsw + _i * 8192), 16, 0, 0); } while (0)
; #define PG8_LDA(dst, b, h) do { _Pragma("unroll") for (int m = 0; m < 4; ++m) _Pragma("unroll") for (int k = 0; k < 2; ++k) dst[m][k] = *(const PG8_LAS bf16x8*)(lds + PG8_SA(b, h) + aoff + m * 2048 + k * 1024); } while (0)
; #define PG8_LDB(dst, b, h) do { _Pragma("unroll") for (int n = 0; n < 2; ++n) _Pragma("unroll") for (int k = 0; k < 2; ++k) dst[n][k] = *(const PG8_LAS bf16x8*)(lds + PG8_SB(b, h) + boff + n * 2048 + k * 1024); } while (0)
; #define PG8_MMA(ai, bj, At, Bt) do { __builtin_amdgcn_s_setprio(1); _Pragma("unroll") for (int m = 0; m < 4; ++m) _Pragma("unroll") for (int n = 0; n < 2; ++n) _Pragma("unroll") for (int k = 0; k < 2; ++k) \
;         acc[ai][bj][m][n] = __builtin_amdgcn_mfma_f32_16x16x32_bf16(Bt[n][k], At[m][k], acc[ai][bj][m][n], 0, 0, 0); __builtin_amdgcn_s_setprio(0); } while (0)
; #define PG8_WAIT_V(n) asm volatile("s_waitcnt vmcnt(" #n ")" ::: "memory")
; #define PG8_WAIT_L(n) asm volatile("s_waitcnt lgkmcnt(" #n ")" ::: "memory")
; #define PG8_BAR __builtin_amdgcn_s_barrier()
; #define PG8_SCHED __builtin_amdgcn_sched_barrier(0)
; template <class Epi, class Sched, bool ALIGN_EPI = false, bool SP2 = false>
; __device__ __forceinline__ void gemm_phase(PG8_LAS unsigned char* lds, const Gemm g, const Sched& S, const Epi& E) {
;     ...
;             PG8_LDB(B0, 1, 0); PG8_LDB(B1, 1, 1); PG8_SCHED; PG8_LDA(At, 1, 0); PG8_STAGE(PG8_SA(0, 0), a2, voffA); PG8_STAGE(PG8_SA(0, 1), a2 + hstep, voffA);
;             PG8_WAIT_V(8); PG8_WAIT_L(0); PG8_BAR; PG8_MMA(0, 0, At, B0); PG8_MMA(0, 1, At, B1); PG8_BAR; PG8_SCHED;
;             PG8_LDA(At, 1, 1); PG8_STAGE(PG8_SB(1, 0), b3, voffB); PG8_STAGE(PG8_SB(1, 1), b3 + hstep, voffB); (void)a3;
;             PG8_WAIT_V(6); PG8_WAIT_L(0); PG8_BAR; PG8_MMA(1, 0, At, B0); PG8_MMA(1, 1, At, B1); PG8_BAR; PG8_SCHED;
.Lpl_vt:
	s_add_i32 s53, 0, 0x18000
	s_add_i32 s92, 0, 0x1c000
	v_add_u32_e32 v154, s53, v161
	v_add_u32_e32 v176, s92, v161
	ds_read_b128 v[100:103], v154
	ds_read_b128 v[104:107], v154 offset:1024
	ds_read_b128 v[108:111], v154 offset:2048
	ds_read_b128 v[154:157], v154 offset:3072
	ds_read_b128 v[164:167], v176
	ds_read_b128 v[168:171], v176 offset:1024
	ds_read_b128 v[172:175], v176 offset:2048
	ds_read_b128 v[176:179], v176 offset:3072
	s_mov_b32 m0, s57
	v_lshl_add_u64 v[208:209], s[94:95], 0, v[148:149]
	s_add_u32 s78, s94, 0x80000
	ds_read_b128 v[180:183], v163 offset:32768
	ds_read_b128 v[184:187], v163 offset:33792
	ds_read_b128 v[188:191], v163 offset:34816
	ds_read_b128 v[192:195], v163 offset:35840
	ds_read_b128 v[196:199], v163 offset:36864
	ds_read_b128 v[200:203], v163 offset:37888
	ds_read_b128 v[218:221], v163 offset:38912
	ds_read_b128 v[232:235], v163 offset:39936
	global_load_lds_dwordx4 v[208:209], off
	v_lshl_add_u64 v[208:209], s[94:95], 0, v[146:147]
	s_mov_b32 m0, s84
	s_addc_u32 s79, s95, 0
	global_load_lds_dwordx4 v[208:209], off
	v_lshl_add_u64 v[208:209], s[78:79], 0, v[148:149]
	s_mov_b32 m0, s97
	s_nop 0
	global_load_lds_dwordx4 v[208:209], off
	v_lshl_add_u64 v[208:209], s[78:79], 0, v[146:147]
	s_mov_b32 m0, s34
	s_nop 0
	global_load_lds_dwordx4 v[208:209], off
	s_waitcnt vmcnt(8)
	s_waitcnt lgkmcnt(0)
	s_barrier
	v_mfma_f32_16x16x32_bf16 v[140:143], v[100:103], v[180:183], v[140:143]
	v_mfma_f32_16x16x32_bf16 v[136:139], v[108:111], v[180:183], v[136:139]
	v_mfma_f32_16x16x32_bf16 v[124:127], v[100:103], v[188:191], v[124:127]
	v_mfma_f32_16x16x32_bf16 v[120:123], v[108:111], v[188:191], v[120:123]
	v_mfma_f32_16x16x32_bf16 v[92:95], v[100:103], v[196:199], v[92:95]
	v_mfma_f32_16x16x32_bf16 v[88:91], v[108:111], v[196:199], v[88:91]
	v_mfma_f32_16x16x32_bf16 v[76:79], v[100:103], v[218:221], v[76:79]
	v_mfma_f32_16x16x32_bf16 v[72:75], v[108:111], v[218:221], v[72:75]
	v_mfma_f32_16x16x32_bf16 v[140:143], v[104:107], v[184:187], v[140:143]
	v_mfma_f32_16x16x32_bf16 v[136:139], v[154:157], v[184:187], v[136:139]
	v_mfma_f32_16x16x32_bf16 v[124:127], v[104:107], v[192:195], v[124:127]
	v_mfma_f32_16x16x32_bf16 v[120:123], v[154:157], v[192:195], v[120:123]
	v_mfma_f32_16x16x32_bf16 v[92:95], v[104:107], v[200:203], v[92:95]
	v_mfma_f32_16x16x32_bf16 v[88:91], v[154:157], v[200:203], v[88:91]
	v_mfma_f32_16x16x32_bf16 v[76:79], v[104:107], v[232:235], v[76:79]
	v_mfma_f32_16x16x32_bf16 v[72:75], v[154:157], v[232:235], v[72:75]
	v_mfma_f32_16x16x32_bf16 v[132:135], v[164:167], v[180:183], v[132:135]
	v_mfma_f32_16x16x32_bf16 v[128:131], v[172:175], v[180:183], v[128:131]
	v_mfma_f32_16x16x32_bf16 v[116:119], v[164:167], v[188:191], v[116:119]
	v_mfma_f32_16x16x32_bf16 v[112:115], v[172:175], v[188:191], v[112:115]
	v_mfma_f32_16x16x32_bf16 v[84:87], v[164:167], v[196:199], v[84:87]
	v_mfma_f32_16x16x32_bf16 v[80:83], v[172:175], v[196:199], v[80:83]
	v_mfma_f32_16x16x32_bf16 v[68:71], v[164:167], v[218:221], v[68:71]
	v_mfma_f32_16x16x32_bf16 v[64:67], v[172:175], v[218:221], v[64:67]
	v_mfma_f32_16x16x32_bf16 v[132:135], v[168:171], v[184:187], v[132:135]
	v_mfma_f32_16x16x32_bf16 v[128:131], v[176:179], v[184:187], v[128:131]
	v_mfma_f32_16x16x32_bf16 v[116:119], v[168:171], v[192:195], v[116:119]
	v_mfma_f32_16x16x32_bf16 v[112:115], v[176:179], v[192:195], v[112:115]
	v_mfma_f32_16x16x32_bf16 v[84:87], v[168:171], v[200:203], v[84:87]
	v_mfma_f32_16x16x32_bf16 v[80:83], v[176:179], v[200:203], v[80:83]
	v_mfma_f32_16x16x32_bf16 v[68:71], v[168:171], v[232:235], v[68:71]
	v_mfma_f32_16x16x32_bf16 v[64:67], v[176:179], v[232:235], v[64:67]
	s_barrier
	s_add_i32 s53, s53, s23
	v_lshl_add_u64 v[158:159], v[158:159], 0, s[26:27]
	s_mov_b32 m0, s53
	ds_read_b128 v[180:183], v163 offset:49152
	ds_read_b128 v[184:187], v163 offset:50176
	ds_read_b128 v[188:191], v163 offset:51200
	ds_read_b128 v[192:195], v163 offset:52224
	ds_read_b128 v[196:199], v163 offset:53248
	ds_read_b128 v[200:203], v163 offset:54272
	ds_read_b128 v[218:221], v163 offset:55296
	ds_read_b128 v[232:235], v163 offset:56320
	global_load_lds_dwordx4 v[158:159], off
	s_add_i32 m0, s53, 0x2000
	s_add_u32 s44, s44, 0x80080
	v_lshl_add_u64 v[158:159], v[206:207], 0, s[26:27]
	s_addc_u32 s45, s45, 0
	s_add_i32 s53, s92, s23
	global_load_lds_dwordx4 v[158:159], off
	v_lshl_add_u64 v[158:159], s[44:45], 0, v[204:205]
	s_mov_b32 m0, s53
	s_nop 0
	global_load_lds_dwordx4 v[158:159], off
	v_lshl_add_u64 v[158:159], s[44:45], 0, v[144:145]
	s_add_i32 m0, s53, 0x2000
	s_nop 0
	global_load_lds_dwordx4 v[158:159], off
	s_waitcnt vmcnt(6)
	s_waitcnt lgkmcnt(0)
	s_barrier
	v_mfma_f32_16x16x32_bf16 v[60:63], v[100:103], v[180:183], v[60:63]
	v_mfma_f32_16x16x32_bf16 v[56:59], v[108:111], v[180:183], v[56:59]
	v_mfma_f32_16x16x32_bf16 v[48:51], v[100:103], v[188:191], v[48:51]
	v_mfma_f32_16x16x32_bf16 v[40:43], v[108:111], v[188:191], v[40:43]
	v_mfma_f32_16x16x32_bf16 v[32:35], v[100:103], v[196:199], v[32:35]
	v_mfma_f32_16x16x32_bf16 v[24:27], v[108:111], v[196:199], v[24:27]
	v_mfma_f32_16x16x32_bf16 v[16:19], v[100:103], v[218:221], v[16:19]
	v_mfma_f32_16x16x32_bf16 v[8:11], v[108:111], v[218:221], v[8:11]
	v_mfma_f32_16x16x32_bf16 v[60:63], v[104:107], v[184:187], v[60:63]
	v_mfma_f32_16x16x32_bf16 v[56:59], v[154:157], v[184:187], v[56:59]
	v_mfma_f32_16x16x32_bf16 v[48:51], v[104:107], v[192:195], v[48:51]
	v_mfma_f32_16x16x32_bf16 v[40:43], v[154:157], v[192:195], v[40:43]
	v_mfma_f32_16x16x32_bf16 v[32:35], v[104:107], v[200:203], v[32:35]
	v_mfma_f32_16x16x32_bf16 v[24:27], v[154:157], v[200:203], v[24:27]
	v_mfma_f32_16x16x32_bf16 v[16:19], v[104:107], v[232:235], v[16:19]
	v_mfma_f32_16x16x32_bf16 v[8:11], v[154:157], v[232:235], v[8:11]
	v_mfma_f32_16x16x32_bf16 v[52:55], v[164:167], v[180:183], v[52:55]
	v_mfma_f32_16x16x32_bf16 v[44:47], v[172:175], v[180:183], v[44:47]
	v_mfma_f32_16x16x32_bf16 v[36:39], v[164:167], v[188:191], v[36:39]
	v_mfma_f32_16x16x32_bf16 v[28:31], v[172:175], v[188:191], v[28:31]
	v_mfma_f32_16x16x32_bf16 v[20:23], v[164:167], v[196:199], v[20:23]
	v_mfma_f32_16x16x32_bf16 v[12:15], v[172:175], v[196:199], v[12:15]
	v_mfma_f32_16x16x32_bf16 v[4:7], v[164:167], v[218:221], v[4:7]
	v_mfma_f32_16x16x32_bf16 v[0:3], v[172:175], v[218:221], v[0:3]
	v_mfma_f32_16x16x32_bf16 v[52:55], v[168:171], v[184:187], v[52:55]
	v_mfma_f32_16x16x32_bf16 v[44:47], v[176:179], v[184:187], v[44:47]
	v_mfma_f32_16x16x32_bf16 v[36:39], v[168:171], v[192:195], v[36:39]
	v_mfma_f32_16x16x32_bf16 v[28:31], v[176:179], v[192:195], v[28:31]
	v_mfma_f32_16x16x32_bf16 v[20:23], v[168:171], v[200:203], v[20:23]
	v_mfma_f32_16x16x32_bf16 v[12:15], v[176:179], v[200:203], v[12:15]
	v_mfma_f32_16x16x32_bf16 v[4:7], v[168:171], v[232:235], v[4:7]
	v_mfma_f32_16x16x32_bf16 v[0:3], v[176:179], v[232:235], v[0:3]
	s_barrier
	s_add_i32 s52, s52, 2
	s_add_u32 s88, s88, 0x100
	s_addc_u32 s89, s89, 0
	s_cmp_gt_u32 s52, 29
	s_cbranch_scc0 .LBB0_232
	s_and_b64 vcc, exec, s[8:9]
	s_cbranch_vccz .LBB0_235
	s_barrier

; #define PG8_STAGE(bufoff, gbase, voff) do { _Pragma("unroll") for (int _i = 0; _i < 2; ++_i) \
;         __builtin_amdgcn_global_load_lds((const unsigned*)((const char*)(gbase) + (voff)[_i]), (PG8_LAS unsigned*)(lds + (bufoff) + ldsw + _i * 8192), 16, 0, 0); } while (0)
; #define PG8_LDA(dst, b, h) do { _Pragma("unroll") for (int m = 0; m < 4; ++m) _Pragma("unroll") for (int k = 0; k < 2; ++k) dst[m][k] = *(const PG8_LAS bf16x8*)(lds + PG8_SA(b, h) + aoff + m * 2048 + k * 1024); } while (0)
; #define PG8_LDB(dst, b, h) do { _Pragma("unroll") for (int n = 0; n < 2; ++n) _Pragma("unroll") for (int k = 0; k < 2; ++k) dst[n][k] = *(const PG8_LAS bf16x8*)(lds + PG8_SB(b, h) + boff + n * 2048 + k * 1024); } while (0)
; #define PG8_MMA(ai, bj, At, Bt) do { __builtin_amdgcn_s_setprio(1); _Pragma("unroll") for (int m = 0; m < 4; ++m) _Pragma("unroll") for (int n = 0; n < 2; ++n) _Pragma("unroll") for (int k = 0; k < 2; ++k) \
;         acc[ai][bj][m][n] = __builtin_amdgcn_mfma_f32_16x16x32_bf16(Bt[n][k], At[m][k], acc[ai][bj][m][n], 0, 0, 0); __builtin_amdgcn_s_setprio(0); } while (0)
; #define PG8_WAIT_V(n) asm volatile("s_waitcnt vmcnt(" #n ")" ::: "memory")
; #define PG8_WAIT_L(n) asm volatile("s_waitcnt lgkmcnt(" #n ")" ::: "memory")
; template <class Epi, class Sched, bool ALIGN_EPI = false, bool SP2 = false>
; __device__ __forceinline__ void gemm_phase(PG8_LAS unsigned char* lds, const Gemm g, const Sched& S, const Epi& E) {
;     ...
;         const bool has_next = S.next(ui + 1, nxt);
;         const char* nA = has_next ? (const char*)g.A + (size_t)nxt.pm * tstep : cA; const char* nB = has_next ? (const char*)g.Bt + (size_t)nxt.pn * tstep : cB;
;         for (int t = 0; t < nt; t += 2) {
;             const bool last = (t == nt - 2);
;             const char* a1 = cA + (size_t)(t + 1) * kstep;
;             const char* a2 = last ? nA : cA + (size_t)(t + 2) * kstep; const char* b2 = last ? nB : cB + (size_t)(t + 2) * kstep;
;             const char* a3 = a2 + kstep; const char* b3 = b2 + kstep;
;             if (last && has_next) S.a_ready(nxt);
;             if constexpr (SP2) {
;             PG8_LDB(B0, 0, 0); PG8_LDB(B1, 0, 1); PG8_SCHED; PG8_LDA(At, 0, 0); PG8_STAGE(PG8_SA(1, 0), a1, voffA); PG8_STAGE(PG8_SA(1, 1), a1 + hstep, voffA);
;             PG8_WAIT_V(8); PG8_WAIT_L(0); PG8_BAR; PG8_MMA(0, 0, At, B0); PG8_MMA(0, 1, At, B1); PG8_BAR; PG8_SCHED;
.LBB0_425:
	s_ashr_i32 s47, s46, 31
	s_lshl_b64 s[52:53], s[46:47], 20
	s_add_u32 s72, s98, s52
	s_addc_u32 s73, s99, s53
	s_and_b64 s[52:53], s[38:39], exec
	s_cselect_b32 s47, s73, s17
	s_cselect_b32 s68, s72, s16
	s_ashr_i32 s43, s42, 31
	s_lshl_b64 s[52:53], s[42:43], 20
	s_add_u32 s76, s20, s52
	s_addc_u32 s77, s21, s53
	s_and_b64 s[52:53], s[38:39], exec
	s_cselect_b32 s43, s77, s45
	s_cselect_b32 s69, s76, s44
	s_add_u32 s70, s44, 0x100
	s_addc_u32 s71, s45, 0
	v_lshl_add_u64 v[138:139], s[16:17], 0, v[134:135]
	v_lshl_add_u64 v[140:141], s[16:17], 0, v[136:137]
	s_mov_b32 s52, -2
	s_mov_b64 s[88:89], 0
	s_add_u32 s44, s16, s88
	s_addc_u32 s45, s17, s89
	s_add_u32 s53, s44, 0x100
	s_addc_u32 s78, s45, 0
	s_add_u32 s44, s70, s88
	s_addc_u32 s45, s71, s89
	s_add_i32 s79, 0, 0x10000
	s_cmpk_eq_i32 s88, 0xf00
	s_cselect_b32 s45, s43, s45
	s_cselect_b32 s44, s69, s44
	s_cselect_b32 s95, s47, s78
	s_cselect_b32 s94, s68, s53
	s_add_i32 s53, 0, 0x14000
	v_add_u32_e32 v158, s79, v143
	v_add_u32_e32 v174, s53, v143
	ds_read_b128 v[146:149], v158
	ds_read_b128 v[150:153], v158 offset:1024
	ds_read_b128 v[154:157], v158 offset:2048
	ds_read_b128 v[158:161], v158 offset:3072
	ds_read_b128 v[162:165], v174
	ds_read_b128 v[166:169], v174 offset:1024
	ds_read_b128 v[170:173], v174 offset:2048
	ds_read_b128 v[174:177], v174 offset:3072
	v_lshl_add_u64 v[202:203], v[138:139], 0, s[88:89]
	v_lshl_add_u64 v[222:223], v[202:203], 0, s[26:27]
	s_add_i32 m0, s23, 0x8000
	ds_read_b128 v[178:181], v145
	ds_read_b128 v[182:185], v145 offset:1024
	ds_read_b128 v[186:189], v145 offset:2048
	ds_read_b128 v[190:193], v145 offset:3072
	ds_read_b128 v[194:197], v145 offset:4096
	ds_read_b128 v[198:201], v145 offset:5120
	ds_read_b128 v[206:209], v145 offset:6144
	ds_read_b128 v[218:221], v145 offset:7168
	global_load_lds_dwordx4 v[222:223], off
	v_lshl_add_u64 v[222:223], v[140:141], 0, s[88:89]
	v_lshl_add_u64 v[232:233], v[222:223], 0, s[26:27]
	s_add_i32 m0, s23, 0xa000
	v_lshl_add_u64 v[202:203], v[202:203], 0, s[28:29]
	global_load_lds_dwordx4 v[232:233], off
	s_add_i32 m0, s23, 0xc000
	s_nop 0
	global_load_lds_dwordx4 v[202:203], off
	v_lshl_add_u64 v[202:203], v[222:223], 0, s[28:29]
	s_add_i32 m0, s23, 0xe000
	s_nop 0
	global_load_lds_dwordx4 v[202:203], off
	s_waitcnt vmcnt(8)
	s_waitcnt lgkmcnt(0)
	s_barrier
	v_mfma_f32_16x16x32_bf16 v[124:127], v[146:149], v[178:181], 0
	v_mfma_f32_16x16x32_bf16 v[120:123], v[154:157], v[178:181], 0
	v_mfma_f32_16x16x32_bf16 v[116:119], v[146:149], v[186:189], 0
	v_mfma_f32_16x16x32_bf16 v[108:111], v[154:157], v[186:189], 0
	v_mfma_f32_16x16x32_bf16 v[100:103], v[146:149], v[194:197], 0
	v_mfma_f32_16x16x32_bf16 v[92:95], v[154:157], v[194:197], 0
	v_mfma_f32_16x16x32_bf16 v[84:87], v[146:149], v[206:209], 0
	v_mfma_f32_16x16x32_bf16 v[76:79], v[154:157], v[206:209], 0
	v_mfma_f32_16x16x32_bf16 v[124:127], v[150:153], v[182:185], v[124:127]
	v_mfma_f32_16x16x32_bf16 v[120:123], v[158:161], v[182:185], v[120:123]
	v_mfma_f32_16x16x32_bf16 v[116:119], v[150:153], v[190:193], v[116:119]
	v_mfma_f32_16x16x32_bf16 v[108:111], v[158:161], v[190:193], v[108:111]
	v_mfma_f32_16x16x32_bf16 v[100:103], v[150:153], v[198:201], v[100:103]
	v_mfma_f32_16x16x32_bf16 v[92:95], v[158:161], v[198:201], v[92:95]
	v_mfma_f32_16x16x32_bf16 v[84:87], v[150:153], v[218:221], v[84:87]
	v_mfma_f32_16x16x32_bf16 v[76:79], v[158:161], v[218:221], v[76:79]
	v_mfma_f32_16x16x32_bf16 v[112:115], v[162:165], v[178:181], 0
	v_mfma_f32_16x16x32_bf16 v[104:107], v[170:173], v[178:181], 0
	v_mfma_f32_16x16x32_bf16 v[96:99], v[162:165], v[186:189], 0
	v_mfma_f32_16x16x32_bf16 v[88:91], v[170:173], v[186:189], 0
	v_mfma_f32_16x16x32_bf16 v[80:83], v[162:165], v[194:197], 0
	v_mfma_f32_16x16x32_bf16 v[72:75], v[170:173], v[194:197], 0
	v_mfma_f32_16x16x32_bf16 v[68:71], v[162:165], v[206:209], 0
	v_mfma_f32_16x16x32_bf16 v[64:67], v[170:173], v[206:209], 0
	v_mfma_f32_16x16x32_bf16 v[112:115], v[166:169], v[182:185], v[112:115]
	v_mfma_f32_16x16x32_bf16 v[104:107], v[174:177], v[182:185], v[104:107]
	v_mfma_f32_16x16x32_bf16 v[96:99], v[166:169], v[190:193], v[96:99]
	v_mfma_f32_16x16x32_bf16 v[88:91], v[174:177], v[190:193], v[88:91]
	v_mfma_f32_16x16x32_bf16 v[80:83], v[166:169], v[198:201], v[80:83]
	v_mfma_f32_16x16x32_bf16 v[72:75], v[174:177], v[198:201], v[72:75]
	v_mfma_f32_16x16x32_bf16 v[68:71], v[166:169], v[218:221], v[68:71]
	v_mfma_f32_16x16x32_bf16 v[64:67], v[174:177], v[218:221], v[64:67]
	s_barrier
; #define PG8_STAGE(bufoff, gbase, voff) do { _Pragma("unroll") for (int _i = 0; _i < 2; ++_i) \
;         __builtin_amdgcn_global_load_lds((const unsigned*)((const char*)(gbase) + (voff)[_i]), (PG8_LAS unsigned*)(lds + (bufoff) + ldsw + _i * 8192), 16, 0, 0); } while (0)
; #define PG8_LDA(dst, b, h) do { _Pragma("unroll") for (int m = 0; m < 4; ++m) _Pragma("unroll") for (int k = 0; k < 2; ++k) dst[m][k] = *(const PG8_LAS bf16x8*)(lds + PG8_SA(b, h) + aoff + m * 2048 + k * 1024); } while (0)
; #define PG8_MMA(ai, bj, At, Bt) do { __builtin_amdgcn_s_setprio(1); _Pragma("unroll") for (int m = 0; m < 4; ++m) _Pragma("unroll") for (int n = 0; n < 2; ++n) _Pragma("unroll") for (int k = 0; k < 2; ++k) \
;         acc[ai][bj][m][n] = __builtin_amdgcn_mfma_f32_16x16x32_bf16(Bt[n][k], At[m][k], acc[ai][bj][m][n], 0, 0, 0); __builtin_amdgcn_s_setprio(0); } while (0)
; #define PG8_WAIT_V(n) asm volatile("s_waitcnt vmcnt(" #n ")" ::: "memory")
; #define PG8_WAIT_L(n) asm volatile("s_waitcnt lgkmcnt(" #n ")" ::: "memory")
; #define PG8_BAR __builtin_amdgcn_s_barrier()
; #define PG8_SCHED __builtin_amdgcn_sched_barrier(0)
; template <class Epi, class Sched, bool ALIGN_EPI = false, bool SP2 = false>
; __device__ __forceinline__ void gemm_phase(PG8_LAS unsigned char* lds, const Gemm g, const Sched& S, const Epi& E) {
;     ...
;             PG8_LDA(At, 0, 1); PG8_STAGE(PG8_SB(0, 0), b2, voffB); PG8_STAGE(PG8_SB(0, 1), b2 + hstep, voffB);
;             PG8_WAIT_V(6); PG8_WAIT_L(0); PG8_BAR; PG8_MMA(1, 0, At, B0); PG8_MMA(1, 1, At, B1); PG8_BAR; PG8_SCHED;
	s_add_i32 s78, s79, s22
	v_lshl_add_u64 v[202:203], s[44:45], 0, v[204:205]
	s_mov_b32 m0, s78
	ds_read_b128 v[178:181], v145 offset:16384
	ds_read_b128 v[182:185], v145 offset:17408
	ds_read_b128 v[186:189], v145 offset:18432
	ds_read_b128 v[190:193], v145 offset:19456
	ds_read_b128 v[194:197], v145 offset:20480
	ds_read_b128 v[198:201], v145 offset:21504
	ds_read_b128 v[206:209], v145 offset:22528
	ds_read_b128 v[218:221], v145 offset:23552
	global_load_lds_dwordx4 v[202:203], off
	s_add_i32 m0, s78, 0x2000
	s_add_u32 s78, s44, 0x80000
	v_lshl_add_u64 v[222:223], s[44:45], 0, v[128:129]
	s_addc_u32 s79, s45, 0
	s_add_i32 s53, s53, s22
	global_load_lds_dwordx4 v[222:223], off
	v_lshl_add_u64 v[232:233], s[78:79], 0, v[204:205]
	s_mov_b32 m0, s53
	s_nop 0
	global_load_lds_dwordx4 v[232:233], off
	v_lshl_add_u64 v[232:233], s[78:79], 0, v[128:129]
	s_add_i32 m0, s53, 0x2000
	s_nop 0
	global_load_lds_dwordx4 v[232:233], off
	s_waitcnt vmcnt(6)
	s_waitcnt lgkmcnt(0)
	s_barrier
	v_mfma_f32_16x16x32_bf16 v[60:63], v[146:149], v[178:181], 0
	v_mfma_f32_16x16x32_bf16 v[56:59], v[154:157], v[178:181], 0
	v_mfma_f32_16x16x32_bf16 v[52:55], v[146:149], v[186:189], 0
	v_mfma_f32_16x16x32_bf16 v[44:47], v[154:157], v[186:189], 0
	v_mfma_f32_16x16x32_bf16 v[36:39], v[146:149], v[194:197], 0
	v_mfma_f32_16x16x32_bf16 v[28:31], v[154:157], v[194:197], 0
	v_mfma_f32_16x16x32_bf16 v[20:23], v[146:149], v[206:209], 0
	v_mfma_f32_16x16x32_bf16 v[12:15], v[154:157], v[206:209], 0
	v_mfma_f32_16x16x32_bf16 v[60:63], v[150:153], v[182:185], v[60:63]
	v_mfma_f32_16x16x32_bf16 v[56:59], v[158:161], v[182:185], v[56:59]
	v_mfma_f32_16x16x32_bf16 v[52:55], v[150:153], v[190:193], v[52:55]
	v_mfma_f32_16x16x32_bf16 v[44:47], v[158:161], v[190:193], v[44:47]
	v_mfma_f32_16x16x32_bf16 v[36:39], v[150:153], v[198:201], v[36:39]
	v_mfma_f32_16x16x32_bf16 v[28:31], v[158:161], v[198:201], v[28:31]
	v_mfma_f32_16x16x32_bf16 v[20:23], v[150:153], v[218:221], v[20:23]
	v_mfma_f32_16x16x32_bf16 v[12:15], v[158:161], v[218:221], v[12:15]
	v_mfma_f32_16x16x32_bf16 v[48:51], v[162:165], v[178:181], 0
	v_mfma_f32_16x16x32_bf16 v[40:43], v[170:173], v[178:181], 0
	v_mfma_f32_16x16x32_bf16 v[32:35], v[162:165], v[186:189], 0
	v_mfma_f32_16x16x32_bf16 v[24:27], v[170:173], v[186:189], 0
	v_mfma_f32_16x16x32_bf16 v[16:19], v[162:165], v[194:197], 0
	v_mfma_f32_16x16x32_bf16 v[8:11], v[170:173], v[194:197], 0
	v_mfma_f32_16x16x32_bf16 v[4:7], v[162:165], v[206:209], 0
	v_mfma_f32_16x16x32_bf16 v[0:3], v[170:173], v[206:209], 0
	v_mfma_f32_16x16x32_bf16 v[48:51], v[166:169], v[182:185], v[48:51]
	v_mfma_f32_16x16x32_bf16 v[40:43], v[174:177], v[182:185], v[40:43]
	v_mfma_f32_16x16x32_bf16 v[32:35], v[166:169], v[190:193], v[32:35]
	v_mfma_f32_16x16x32_bf16 v[24:27], v[174:177], v[190:193], v[24:27]
	v_mfma_f32_16x16x32_bf16 v[16:19], v[166:169], v[198:201], v[16:19]
	v_mfma_f32_16x16x32_bf16 v[8:11], v[174:177], v[198:201], v[8:11]
	v_mfma_f32_16x16x32_bf16 v[4:7], v[166:169], v[218:221], v[4:7]
	v_mfma_f32_16x16x32_bf16 v[0:3], v[174:177], v[218:221], v[0:3]
	s_barrier
	s_branch .Lpl_o

; #define PG8_STAGE(bufoff, gbase, voff) do { _Pragma("unroll") for (int _i = 0; _i < 2; ++_i) \
;         __builtin_amdgcn_global_load_lds((const unsigned*)((const char*)(gbase) + (voff)[_i]), (PG8_LAS unsigned*)(lds + (bufoff) + ldsw + _i * 8192), 16, 0, 0); } while (0)
; #define PG8_LDA(dst, b, h) do { _Pragma("unroll") for (int m = 0; m < 4; ++m) _Pragma("unroll") for (int k = 0; k < 2; ++k) dst[m][k] = *(const PG8_LAS bf16x8*)(lds + PG8_SA(b, h) + aoff + m * 2048 + k * 1024); } while (0)
; #define PG8_LDB(dst, b, h) do { _Pragma("unroll") for (int n = 0; n < 2; ++n) _Pragma("unroll") for (int k = 0; k < 2; ++k) dst[n][k] = *(const PG8_LAS bf16x8*)(lds + PG8_SB(b, h) + boff + n * 2048 + k * 1024); } while (0)
; #define PG8_MMA(ai, bj, At, Bt) do { __builtin_amdgcn_s_setprio(1); _Pragma("unroll") for (int m = 0; m < 4; ++m) _Pragma("unroll") for (int n = 0; n < 2; ++n) _Pragma("unroll") for (int k = 0; k < 2; ++k) \
;         acc[ai][bj][m][n] = __builtin_amdgcn_mfma_f32_16x16x32_bf16(Bt[n][k], At[m][k], acc[ai][bj][m][n], 0, 0, 0); __builtin_amdgcn_s_setprio(0); } while (0)
; #define PG8_WAIT_V(n) asm volatile("s_waitcnt vmcnt(" #n ")" ::: "memory")
; #define PG8_WAIT_L(n) asm volatile("s_waitcnt lgkmcnt(" #n ")" ::: "memory")
; #define PG8_BAR __builtin_amdgcn_s_barrier()
; #define PG8_SCHED __builtin_amdgcn_sched_barrier(0)
; template <class Epi, class Sched, bool ALIGN_EPI = false, bool SP2 = false>
; __device__ __forceinline__ void gemm_phase(PG8_LAS unsigned char* lds, const Gemm g, const Sched& S, const Epi& E) {
;     ...
;             PG8_LDB(B0, 1, 0); PG8_LDB(B1, 1, 1); PG8_SCHED; PG8_LDA(At, 1, 0); PG8_STAGE(PG8_SA(0, 0), a2, voffA); PG8_STAGE(PG8_SA(0, 1), a2 + hstep, voffA);
;             PG8_WAIT_V(8); PG8_WAIT_L(0); PG8_BAR; PG8_MMA(0, 0, At, B0); PG8_MMA(0, 1, At, B1); PG8_BAR; PG8_SCHED;
;             PG8_LDA(At, 1, 1); PG8_STAGE(PG8_SB(1, 0), b3, voffB); PG8_STAGE(PG8_SB(1, 1), b3 + hstep, voffB); (void)a3;
;             PG8_WAIT_V(6); PG8_WAIT_L(0); PG8_BAR; PG8_MMA(1, 0, At, B0); PG8_MMA(1, 1, At, B1); PG8_BAR; PG8_SCHED;
.Lpl_o:
	s_add_i32 s53, 0, 0x18000
	s_add_i32 s84, 0, 0x1c000
	v_add_u32_e32 v158, s53, v143
	v_add_u32_e32 v174, s84, v143
	ds_read_b128 v[146:149], v158
	ds_read_b128 v[150:153], v158 offset:1024
	ds_read_b128 v[154:157], v158 offset:2048
	ds_read_b128 v[158:161], v158 offset:3072
	ds_read_b128 v[162:165], v174
	ds_read_b128 v[166:169], v174 offset:1024
	ds_read_b128 v[170:173], v174 offset:2048
	ds_read_b128 v[174:177], v174 offset:3072
	s_mov_b32 m0, s23
	v_lshl_add_u64 v[232:233], s[94:95], 0, v[132:133]
	s_add_u32 s78, s94, 0x80000
	ds_read_b128 v[178:181], v145 offset:32768
	ds_read_b128 v[182:185], v145 offset:33792
	ds_read_b128 v[186:189], v145 offset:34816
	ds_read_b128 v[190:193], v145 offset:35840
	ds_read_b128 v[194:197], v145 offset:36864
	ds_read_b128 v[198:201], v145 offset:37888
	ds_read_b128 v[206:209], v145 offset:38912
	ds_read_b128 v[218:221], v145 offset:39936
	global_load_lds_dwordx4 v[232:233], off
	v_lshl_add_u64 v[232:233], s[94:95], 0, v[130:131]
	s_mov_b32 m0, s34
	s_addc_u32 s79, s95, 0
	global_load_lds_dwordx4 v[232:233], off
	v_lshl_add_u64 v[232:233], s[78:79], 0, v[132:133]
	s_mov_b32 m0, s35
	s_nop 0
	global_load_lds_dwordx4 v[232:233], off
	v_lshl_add_u64 v[232:233], s[78:79], 0, v[130:131]
	s_mov_b32 m0, s36
	s_nop 0
	global_load_lds_dwordx4 v[232:233], off
	s_waitcnt vmcnt(8)
	s_waitcnt lgkmcnt(0)
	s_barrier
	v_mfma_f32_16x16x32_bf16 v[124:127], v[146:149], v[178:181], v[124:127]
	v_mfma_f32_16x16x32_bf16 v[120:123], v[154:157], v[178:181], v[120:123]
	v_mfma_f32_16x16x32_bf16 v[116:119], v[146:149], v[186:189], v[116:119]
	v_mfma_f32_16x16x32_bf16 v[108:111], v[154:157], v[186:189], v[108:111]
	v_mfma_f32_16x16x32_bf16 v[100:103], v[146:149], v[194:197], v[100:103]
	v_mfma_f32_16x16x32_bf16 v[92:95], v[154:157], v[194:197], v[92:95]
	v_mfma_f32_16x16x32_bf16 v[84:87], v[146:149], v[206:209], v[84:87]
	v_mfma_f32_16x16x32_bf16 v[76:79], v[154:157], v[206:209], v[76:79]
	v_mfma_f32_16x16x32_bf16 v[124:127], v[150:153], v[182:185], v[124:127]
	v_mfma_f32_16x16x32_bf16 v[120:123], v[158:161], v[182:185], v[120:123]
	v_mfma_f32_16x16x32_bf16 v[116:119], v[150:153], v[190:193], v[116:119]
	v_mfma_f32_16x16x32_bf16 v[108:111], v[158:161], v[190:193], v[108:111]
	v_mfma_f32_16x16x32_bf16 v[100:103], v[150:153], v[198:201], v[100:103]
	v_mfma_f32_16x16x32_bf16 v[92:95], v[158:161], v[198:201], v[92:95]
	v_mfma_f32_16x16x32_bf16 v[84:87], v[150:153], v[218:221], v[84:87]
	v_mfma_f32_16x16x32_bf16 v[76:79], v[158:161], v[218:221], v[76:79]
	v_mfma_f32_16x16x32_bf16 v[112:115], v[162:165], v[178:181], v[112:115]
	v_mfma_f32_16x16x32_bf16 v[104:107], v[170:173], v[178:181], v[104:107]
	v_mfma_f32_16x16x32_bf16 v[96:99], v[162:165], v[186:189], v[96:99]
	v_mfma_f32_16x16x32_bf16 v[88:91], v[170:173], v[186:189], v[88:91]
	v_mfma_f32_16x16x32_bf16 v[80:83], v[162:165], v[194:197], v[80:83]
	v_mfma_f32_16x16x32_bf16 v[72:75], v[170:173], v[194:197], v[72:75]
	v_mfma_f32_16x16x32_bf16 v[68:71], v[162:165], v[206:209], v[68:71]
	v_mfma_f32_16x16x32_bf16 v[64:67], v[170:173], v[206:209], v[64:67]
	v_mfma_f32_16x16x32_bf16 v[112:115], v[166:169], v[182:185], v[112:115]
	v_mfma_f32_16x16x32_bf16 v[104:107], v[174:177], v[182:185], v[104:107]
	v_mfma_f32_16x16x32_bf16 v[96:99], v[166:169], v[190:193], v[96:99]
	v_mfma_f32_16x16x32_bf16 v[88:91], v[174:177], v[190:193], v[88:91]
	v_mfma_f32_16x16x32_bf16 v[80:83], v[166:169], v[198:201], v[80:83]
	v_mfma_f32_16x16x32_bf16 v[72:75], v[174:177], v[198:201], v[72:75]
	v_mfma_f32_16x16x32_bf16 v[68:71], v[166:169], v[218:221], v[68:71]
	v_mfma_f32_16x16x32_bf16 v[64:67], v[174:177], v[218:221], v[64:67]
	s_barrier
	s_add_i32 s53, s53, s22
	v_lshl_add_u64 v[202:203], v[202:203], 0, s[26:27]
	s_mov_b32 m0, s53
	ds_read_b128 v[178:181], v145 offset:49152
	ds_read_b128 v[182:185], v145 offset:50176
	ds_read_b128 v[186:189], v145 offset:51200
	ds_read_b128 v[190:193], v145 offset:52224
	ds_read_b128 v[194:197], v145 offset:53248
	ds_read_b128 v[198:201], v145 offset:54272
	ds_read_b128 v[206:209], v145 offset:55296
	ds_read_b128 v[218:221], v145 offset:56320
	global_load_lds_dwordx4 v[202:203], off
	s_add_i32 m0, s53, 0x2000
	s_add_u32 s44, s44, 0x80080
	v_lshl_add_u64 v[202:203], v[222:223], 0, s[26:27]
	s_addc_u32 s45, s45, 0
	s_add_i32 s53, s84, s22
	global_load_lds_dwordx4 v[202:203], off
	v_lshl_add_u64 v[202:203], s[44:45], 0, v[204:205]
	s_mov_b32 m0, s53
	s_nop 0
	global_load_lds_dwordx4 v[202:203], off
	v_lshl_add_u64 v[202:203], s[44:45], 0, v[128:129]
	s_add_i32 m0, s53, 0x2000
	s_nop 0
	global_load_lds_dwordx4 v[202:203], off
	s_waitcnt vmcnt(6)
	s_waitcnt lgkmcnt(0)
	s_barrier
	v_mfma_f32_16x16x32_bf16 v[60:63], v[146:149], v[178:181], v[60:63]
	v_mfma_f32_16x16x32_bf16 v[56:59], v[154:157], v[178:181], v[56:59]
	v_mfma_f32_16x16x32_bf16 v[52:55], v[146:149], v[186:189], v[52:55]
	v_mfma_f32_16x16x32_bf16 v[44:47], v[154:157], v[186:189], v[44:47]
	v_mfma_f32_16x16x32_bf16 v[36:39], v[146:149], v[194:197], v[36:39]
	v_mfma_f32_16x16x32_bf16 v[28:31], v[154:157], v[194:197], v[28:31]
	v_mfma_f32_16x16x32_bf16 v[20:23], v[146:149], v[206:209], v[20:23]
	v_mfma_f32_16x16x32_bf16 v[12:15], v[154:157], v[206:209], v[12:15]
	v_mfma_f32_16x16x32_bf16 v[60:63], v[150:153], v[182:185], v[60:63]
	v_mfma_f32_16x16x32_bf16 v[56:59], v[158:161], v[182:185], v[56:59]
	v_mfma_f32_16x16x32_bf16 v[52:55], v[150:153], v[190:193], v[52:55]
	v_mfma_f32_16x16x32_bf16 v[44:47], v[158:161], v[190:193], v[44:47]
	v_mfma_f32_16x16x32_bf16 v[36:39], v[150:153], v[198:201], v[36:39]
	v_mfma_f32_16x16x32_bf16 v[28:31], v[158:161], v[198:201], v[28:31]
	v_mfma_f32_16x16x32_bf16 v[20:23], v[150:153], v[218:221], v[20:23]
	v_mfma_f32_16x16x32_bf16 v[12:15], v[158:161], v[218:221], v[12:15]
	v_mfma_f32_16x16x32_bf16 v[48:51], v[162:165], v[178:181], v[48:51]
	v_mfma_f32_16x16x32_bf16 v[40:43], v[170:173], v[178:181], v[40:43]
	v_mfma_f32_16x16x32_bf16 v[32:35], v[162:165], v[186:189], v[32:35]
	v_mfma_f32_16x16x32_bf16 v[24:27], v[170:173], v[186:189], v[24:27]
	v_mfma_f32_16x16x32_bf16 v[16:19], v[162:165], v[194:197], v[16:19]
	v_mfma_f32_16x16x32_bf16 v[8:11], v[170:173], v[194:197], v[8:11]
	v_mfma_f32_16x16x32_bf16 v[4:7], v[162:165], v[206:209], v[4:7]
	v_mfma_f32_16x16x32_bf16 v[0:3], v[170:173], v[206:209], v[0:3]
	v_mfma_f32_16x16x32_bf16 v[48:51], v[166:169], v[182:185], v[48:51]
	v_mfma_f32_16x16x32_bf16 v[40:43], v[174:177], v[182:185], v[40:43]
	v_mfma_f32_16x16x32_bf16 v[32:35], v[166:169], v[190:193], v[32:35]
	v_mfma_f32_16x16x32_bf16 v[24:27], v[174:177], v[190:193], v[24:27]
	v_mfma_f32_16x16x32_bf16 v[16:19], v[166:169], v[198:201], v[16:19]
	v_mfma_f32_16x16x32_bf16 v[8:11], v[174:177], v[198:201], v[8:11]
	v_mfma_f32_16x16x32_bf16 v[4:7], v[166:169], v[218:221], v[4:7]
	v_mfma_f32_16x16x32_bf16 v[0:3], v[174:177], v[218:221], v[0:3]
	s_barrier
	s_add_i32 s52, s52, 2
	s_add_u32 s88, s88, 0x100
	s_addc_u32 s89, s89, 0
	s_cmp_gt_u32 s52, 29
	s_cbranch_scc0 .LBB0_426
	s_and_b64 vcc, exec, s[10:11]
	s_cbranch_vccz .LBB0_429
	s_barrier

; #define PG8_STAGE(bufoff, gbase, voff) do { _Pragma("unroll") for (int _i = 0; _i < 2; ++_i) \
;         __builtin_amdgcn_global_load_lds((const unsigned*)((const char*)(gbase) + (voff)[_i]), (PG8_LAS unsigned*)(lds + (bufoff) + ldsw + _i * 8192), 16, 0, 0); } while (0)
; #define PG8_LDA(dst, b, h) do { _Pragma("unroll") for (int m = 0; m < 4; ++m) _Pragma("unroll") for (int k = 0; k < 2; ++k) dst[m][k] = *(const PG8_LAS bf16x8*)(lds + PG8_SA(b, h) + aoff + m * 2048 + k * 1024); } while (0)
; #define PG8_LDB(dst, b, h) do { _Pragma("unroll") for (int n = 0; n < 2; ++n) _Pragma("unroll") for (int k = 0; k < 2; ++k) dst[n][k] = *(const PG8_LAS bf16x8*)(lds + PG8_SB(b, h) + boff + n * 2048 + k * 1024); } while (0)
; #define PG8_MMA(ai, bj, At, Bt) do { __builtin_amdgcn_s_setprio(1); _Pragma("unroll") for (int m = 0; m < 4; ++m) _Pragma("unroll") for (int n = 0; n < 2; ++n) _Pragma("unroll") for (int k = 0; k < 2; ++k) \
;         acc[ai][bj][m][n] = __builtin_amdgcn_mfma_f32_16x16x32_bf16(Bt[n][k], At[m][k], acc[ai][bj][m][n], 0, 0, 0); __builtin_amdgcn_s_setprio(0); } while (0)
; #define PG8_WAIT_V(n) asm volatile("s_waitcnt vmcnt(" #n ")" ::: "memory")
; #define PG8_WAIT_L(n) asm volatile("s_waitcnt lgkmcnt(" #n ")" ::: "memory")
; template <class Epi, class Sched, bool ALIGN_EPI = false, bool SP2 = false>
; __device__ __forceinline__ void gemm_phase(PG8_LAS unsigned char* lds, const Gemm g, const Sched& S, const Epi& E) {
;     ...
;         const bool has_next = S.next(ui + 1, nxt);
;         const char* nA = has_next ? (const char*)g.A + (size_t)nxt.pm * tstep : cA; const char* nB = has_next ? (const char*)g.Bt + (size_t)nxt.pn * tstep : cB;
;         for (int t = 0; t < nt; t += 2) {
;             const bool last = (t == nt - 2);
;             const char* a1 = cA + (size_t)(t + 1) * kstep;
;             const char* a2 = last ? nA : cA + (size_t)(t + 2) * kstep; const char* b2 = last ? nB : cB + (size_t)(t + 2) * kstep;
;             const char* a3 = a2 + kstep; const char* b3 = b2 + kstep;
;             if (last && has_next) S.a_ready(nxt);
;             if constexpr (SP2) {
;             PG8_LDB(B0, 0, 0); PG8_LDB(B1, 0, 1); PG8_SCHED; PG8_LDA(At, 0, 0); PG8_STAGE(PG8_SA(1, 0), a1, voffA); PG8_STAGE(PG8_SA(1, 1), a1 + hstep, voffA);
;             PG8_WAIT_V(8); PG8_WAIT_L(0); PG8_BAR; PG8_MMA(0, 0, At, B0); PG8_MMA(0, 1, At, B1); PG8_BAR; PG8_SCHED;
.LBB0_604:
	s_ashr_i32 s95, s94, 31
	s_lshl_b64 s[16:17], s[94:95], 20
	s_add_u32 s16, s20, s16
	s_addc_u32 s17, s21, s17
	s_and_b64 s[44:45], s[42:43], exec
	s_cselect_b32 s95, s17, s9
	s_cselect_b32 s70, s16, s8
	s_ashr_i32 s7, s6, 31
	s_lshl_b64 s[44:45], s[6:7], 20
	s_add_u32 s44, s22, s44
	s_addc_u32 s45, s23, s45
	s_and_b64 s[52:53], s[42:43], exec
	s_cselect_b32 s7, s45, s11
	s_cselect_b32 s71, s44, s10
	s_add_u32 s79, s10, 0x100
	v_lshl_add_u64 v[138:139], s[8:9], 0, v[134:135]
	v_lshl_add_u64 v[140:141], s[8:9], 0, v[136:137]
	s_addc_u32 s52, s11, 0
	s_mov_b32 s53, -2
	s_mov_b64 vcc, 0
	v_lshl_add_u32 v240, s35, 8, v142
	v_ashrrev_i32_e32 v241, 31, v240
	v_lshl_add_u64 v[240:241], v[240:241], 2, s[88:89]
	global_load_dword v242, v[240:241], off
	global_load_dword v243, v[240:241], off offset:64
	global_load_dword v244, v[240:241], off offset:128
	global_load_dword v245, v[240:241], off offset:192
	global_load_dword v246, v[240:241], off offset:512
	global_load_dword v247, v[240:241], off offset:576
	global_load_dword v248, v[240:241], off offset:640
	global_load_dword v249, v[240:241], off offset:704
	s_add_u32 s10, s8, vcc_lo
	s_addc_u32 s11, s9, vcc_hi
	s_add_u32 s38, s10, 0x100
	s_addc_u32 s39, s11, 0
	s_add_u32 s10, s79, vcc_lo
	s_addc_u32 s11, s52, vcc_hi
	s_add_i32 s78, 0, 0x10000
	s_cmpk_eq_i32 vcc_lo, 0xf00
	s_cselect_b32 s11, s7, s11
	s_cselect_b32 s10, s71, s10
	s_cselect_b32 s69, s95, s39
	s_cselect_b32 s68, s70, s38
	s_add_i32 s92, 0, 0x14000
	v_add_u32_e32 v158, s78, v143
	v_add_u32_e32 v174, s92, v143
	ds_read_b128 v[146:149], v158
	ds_read_b128 v[150:153], v158 offset:1024
	ds_read_b128 v[154:157], v158 offset:2048
	ds_read_b128 v[158:161], v158 offset:3072
	ds_read_b128 v[162:165], v174
	ds_read_b128 v[166:169], v174 offset:1024
	ds_read_b128 v[170:173], v174 offset:2048
	ds_read_b128 v[174:177], v174 offset:3072
	v_lshl_add_u64 v[202:203], v[140:141], 0, vcc
	v_lshl_add_u64 v[222:223], v[202:203], 0, s[26:27]
	s_add_i32 m0, s37, 0x8000
	ds_read_b128 v[178:181], v145
	ds_read_b128 v[182:185], v145 offset:1024
	ds_read_b128 v[186:189], v145 offset:2048
	ds_read_b128 v[190:193], v145 offset:3072
	ds_read_b128 v[194:197], v145 offset:4096
	ds_read_b128 v[198:201], v145 offset:5120
	ds_read_b128 v[206:209], v145 offset:6144
	ds_read_b128 v[218:221], v145 offset:7168
	global_load_lds_dwordx4 v[222:223], off
	v_lshl_add_u64 v[222:223], v[138:139], 0, vcc
	v_lshl_add_u64 v[232:233], v[222:223], 0, s[26:27]
	s_add_i32 m0, s37, 0xa000
	v_lshl_add_u64 v[202:203], v[202:203], 0, s[28:29]
	global_load_lds_dwordx4 v[232:233], off
	s_add_i32 m0, s37, 0xc000
	s_nop 0
	global_load_lds_dwordx4 v[202:203], off
	v_lshl_add_u64 v[202:203], v[222:223], 0, s[28:29]
	s_add_i32 m0, s37, 0xe000
	s_nop 0
	global_load_lds_dwordx4 v[202:203], off
	s_waitcnt vmcnt(8)
	s_waitcnt lgkmcnt(0)
	s_barrier
	v_mfma_f32_16x16x32_bf16 v[124:127], v[146:149], v[178:181], 0
	v_mfma_f32_16x16x32_bf16 v[120:123], v[154:157], v[178:181], 0
	v_mfma_f32_16x16x32_bf16 v[108:111], v[146:149], v[186:189], 0
	v_mfma_f32_16x16x32_bf16 v[104:107], v[154:157], v[186:189], 0
	v_mfma_f32_16x16x32_bf16 v[92:95], v[146:149], v[194:197], 0
	v_mfma_f32_16x16x32_bf16 v[88:91], v[154:157], v[194:197], 0
	v_mfma_f32_16x16x32_bf16 v[76:79], v[146:149], v[206:209], 0
	v_mfma_f32_16x16x32_bf16 v[72:75], v[154:157], v[206:209], 0
	v_mfma_f32_16x16x32_bf16 v[124:127], v[150:153], v[182:185], v[124:127]
	v_mfma_f32_16x16x32_bf16 v[120:123], v[158:161], v[182:185], v[120:123]
	v_mfma_f32_16x16x32_bf16 v[108:111], v[150:153], v[190:193], v[108:111]
	v_mfma_f32_16x16x32_bf16 v[104:107], v[158:161], v[190:193], v[104:107]
	v_mfma_f32_16x16x32_bf16 v[92:95], v[150:153], v[198:201], v[92:95]
	v_mfma_f32_16x16x32_bf16 v[88:91], v[158:161], v[198:201], v[88:91]
	v_mfma_f32_16x16x32_bf16 v[76:79], v[150:153], v[218:221], v[76:79]
	v_mfma_f32_16x16x32_bf16 v[72:75], v[158:161], v[218:221], v[72:75]
	v_mfma_f32_16x16x32_bf16 v[116:119], v[162:165], v[178:181], 0
	v_mfma_f32_16x16x32_bf16 v[112:115], v[170:173], v[178:181], 0
	v_mfma_f32_16x16x32_bf16 v[100:103], v[162:165], v[186:189], 0
	v_mfma_f32_16x16x32_bf16 v[96:99], v[170:173], v[186:189], 0
	v_mfma_f32_16x16x32_bf16 v[84:87], v[162:165], v[194:197], 0
	v_mfma_f32_16x16x32_bf16 v[80:83], v[170:173], v[194:197], 0
	v_mfma_f32_16x16x32_bf16 v[68:71], v[162:165], v[206:209], 0
	v_mfma_f32_16x16x32_bf16 v[64:67], v[170:173], v[206:209], 0
	v_mfma_f32_16x16x32_bf16 v[116:119], v[166:169], v[182:185], v[116:119]
	v_mfma_f32_16x16x32_bf16 v[112:115], v[174:177], v[182:185], v[112:115]
	v_mfma_f32_16x16x32_bf16 v[100:103], v[166:169], v[190:193], v[100:103]
	v_mfma_f32_16x16x32_bf16 v[96:99], v[174:177], v[190:193], v[96:99]
	v_mfma_f32_16x16x32_bf16 v[84:87], v[166:169], v[198:201], v[84:87]
	v_mfma_f32_16x16x32_bf16 v[80:83], v[174:177], v[198:201], v[80:83]
	v_mfma_f32_16x16x32_bf16 v[68:71], v[166:169], v[218:221], v[68:71]
	v_mfma_f32_16x16x32_bf16 v[64:67], v[174:177], v[218:221], v[64:67]
	s_barrier
; #define PG8_STAGE(bufoff, gbase, voff) do { _Pragma("unroll") for (int _i = 0; _i < 2; ++_i) \
;         __builtin_amdgcn_global_load_lds((const unsigned*)((const char*)(gbase) + (voff)[_i]), (PG8_LAS unsigned*)(lds + (bufoff) + ldsw + _i * 8192), 16, 0, 0); } while (0)
; #define PG8_LDA(dst, b, h) do { _Pragma("unroll") for (int m = 0; m < 4; ++m) _Pragma("unroll") for (int k = 0; k < 2; ++k) dst[m][k] = *(const PG8_LAS bf16x8*)(lds + PG8_SA(b, h) + aoff + m * 2048 + k * 1024); } while (0)
; #define PG8_MMA(ai, bj, At, Bt) do { __builtin_amdgcn_s_setprio(1); _Pragma("unroll") for (int m = 0; m < 4; ++m) _Pragma("unroll") for (int n = 0; n < 2; ++n) _Pragma("unroll") for (int k = 0; k < 2; ++k) \
;         acc[ai][bj][m][n] = __builtin_amdgcn_mfma_f32_16x16x32_bf16(Bt[n][k], At[m][k], acc[ai][bj][m][n], 0, 0, 0); __builtin_amdgcn_s_setprio(0); } while (0)
; #define PG8_WAIT_V(n) asm volatile("s_waitcnt vmcnt(" #n ")" ::: "memory")
; #define PG8_WAIT_L(n) asm volatile("s_waitcnt lgkmcnt(" #n ")" ::: "memory")
; #define PG8_BAR __builtin_amdgcn_s_barrier()
; #define PG8_SCHED __builtin_amdgcn_sched_barrier(0)
; template <class Epi, class Sched, bool ALIGN_EPI = false, bool SP2 = false>
; __device__ __forceinline__ void gemm_phase(PG8_LAS unsigned char* lds, const Gemm g, const Sched& S, const Epi& E) {
;     ...
;             PG8_LDA(At, 0, 1); PG8_STAGE(PG8_SB(0, 0), b2, voffB); PG8_STAGE(PG8_SB(0, 1), b2 + hstep, voffB);
;             PG8_WAIT_V(6); PG8_WAIT_L(0); PG8_BAR; PG8_MMA(1, 0, At, B0); PG8_MMA(1, 1, At, B1); PG8_BAR; PG8_SCHED;
	s_add_i32 s38, s78, s36
	v_lshl_add_u64 v[202:203], s[10:11], 0, v[204:205]
	s_mov_b32 m0, s38
	ds_read_b128 v[178:181], v145 offset:16384
	ds_read_b128 v[182:185], v145 offset:17408
	ds_read_b128 v[186:189], v145 offset:18432
	ds_read_b128 v[190:193], v145 offset:19456
	ds_read_b128 v[194:197], v145 offset:20480
	ds_read_b128 v[198:201], v145 offset:21504
	ds_read_b128 v[206:209], v145 offset:22528
	ds_read_b128 v[218:221], v145 offset:23552
	global_load_lds_dwordx4 v[202:203], off
	s_add_i32 m0, s38, 0x2000
	s_add_u32 s38, s10, 0x80000
	v_lshl_add_u64 v[222:223], s[10:11], 0, v[128:129]
	s_addc_u32 s39, s11, 0
	s_add_i32 s78, s92, s36
	global_load_lds_dwordx4 v[222:223], off
	v_lshl_add_u64 v[232:233], s[38:39], 0, v[204:205]
	s_mov_b32 m0, s78
	s_nop 0
	global_load_lds_dwordx4 v[232:233], off
	v_lshl_add_u64 v[232:233], s[38:39], 0, v[128:129]
	s_add_i32 m0, s78, 0x2000
	s_nop 0
	global_load_lds_dwordx4 v[232:233], off
	s_waitcnt vmcnt(6)
	s_waitcnt lgkmcnt(0)
	s_barrier
	v_mfma_f32_16x16x32_bf16 v[60:63], v[146:149], v[178:181], 0
	v_mfma_f32_16x16x32_bf16 v[56:59], v[154:157], v[178:181], 0
	v_mfma_f32_16x16x32_bf16 v[44:47], v[146:149], v[186:189], 0
	v_mfma_f32_16x16x32_bf16 v[40:43], v[154:157], v[186:189], 0
	v_mfma_f32_16x16x32_bf16 v[28:31], v[146:149], v[194:197], 0
	v_mfma_f32_16x16x32_bf16 v[24:27], v[154:157], v[194:197], 0
	v_mfma_f32_16x16x32_bf16 v[12:15], v[146:149], v[206:209], 0
	v_mfma_f32_16x16x32_bf16 v[8:11], v[154:157], v[206:209], 0
	v_mfma_f32_16x16x32_bf16 v[60:63], v[150:153], v[182:185], v[60:63]
	v_mfma_f32_16x16x32_bf16 v[56:59], v[158:161], v[182:185], v[56:59]
	v_mfma_f32_16x16x32_bf16 v[44:47], v[150:153], v[190:193], v[44:47]
	v_mfma_f32_16x16x32_bf16 v[40:43], v[158:161], v[190:193], v[40:43]
	v_mfma_f32_16x16x32_bf16 v[28:31], v[150:153], v[198:201], v[28:31]
	v_mfma_f32_16x16x32_bf16 v[24:27], v[158:161], v[198:201], v[24:27]
	v_mfma_f32_16x16x32_bf16 v[12:15], v[150:153], v[218:221], v[12:15]
	v_mfma_f32_16x16x32_bf16 v[8:11], v[158:161], v[218:221], v[8:11]
	v_mfma_f32_16x16x32_bf16 v[52:55], v[162:165], v[178:181], 0
	v_mfma_f32_16x16x32_bf16 v[48:51], v[170:173], v[178:181], 0
	v_mfma_f32_16x16x32_bf16 v[36:39], v[162:165], v[186:189], 0
	v_mfma_f32_16x16x32_bf16 v[32:35], v[170:173], v[186:189], 0
	v_mfma_f32_16x16x32_bf16 v[20:23], v[162:165], v[194:197], 0
	v_mfma_f32_16x16x32_bf16 v[16:19], v[170:173], v[194:197], 0
	v_mfma_f32_16x16x32_bf16 v[4:7], v[162:165], v[206:209], 0
	v_mfma_f32_16x16x32_bf16 v[0:3], v[170:173], v[206:209], 0
	v_mfma_f32_16x16x32_bf16 v[52:55], v[166:169], v[182:185], v[52:55]
	v_mfma_f32_16x16x32_bf16 v[48:51], v[174:177], v[182:185], v[48:51]
	v_mfma_f32_16x16x32_bf16 v[36:39], v[166:169], v[190:193], v[36:39]
	v_mfma_f32_16x16x32_bf16 v[32:35], v[174:177], v[190:193], v[32:35]
	v_mfma_f32_16x16x32_bf16 v[20:23], v[166:169], v[198:201], v[20:23]
	v_mfma_f32_16x16x32_bf16 v[16:19], v[174:177], v[198:201], v[16:19]
	v_mfma_f32_16x16x32_bf16 v[4:7], v[166:169], v[218:221], v[4:7]
	v_mfma_f32_16x16x32_bf16 v[0:3], v[174:177], v[218:221], v[0:3]
	s_barrier
	s_branch .Lpl_up

; #define PG8_STAGE(bufoff, gbase, voff) do { _Pragma("unroll") for (int _i = 0; _i < 2; ++_i) \
;         __builtin_amdgcn_global_load_lds((const unsigned*)((const char*)(gbase) + (voff)[_i]), (PG8_LAS unsigned*)(lds + (bufoff) + ldsw + _i * 8192), 16, 0, 0); } while (0)
; #define PG8_LDA(dst, b, h) do { _Pragma("unroll") for (int m = 0; m < 4; ++m) _Pragma("unroll") for (int k = 0; k < 2; ++k) dst[m][k] = *(const PG8_LAS bf16x8*)(lds + PG8_SA(b, h) + aoff + m * 2048 + k * 1024); } while (0)
; #define PG8_LDB(dst, b, h) do { _Pragma("unroll") for (int n = 0; n < 2; ++n) _Pragma("unroll") for (int k = 0; k < 2; ++k) dst[n][k] = *(const PG8_LAS bf16x8*)(lds + PG8_SB(b, h) + boff + n * 2048 + k * 1024); } while (0)
; #define PG8_MMA(ai, bj, At, Bt) do { __builtin_amdgcn_s_setprio(1); _Pragma("unroll") for (int m = 0; m < 4; ++m) _Pragma("unroll") for (int n = 0; n < 2; ++n) _Pragma("unroll") for (int k = 0; k < 2; ++k) \
;         acc[ai][bj][m][n] = __builtin_amdgcn_mfma_f32_16x16x32_bf16(Bt[n][k], At[m][k], acc[ai][bj][m][n], 0, 0, 0); __builtin_amdgcn_s_setprio(0); } while (0)
; #define PG8_WAIT_V(n) asm volatile("s_waitcnt vmcnt(" #n ")" ::: "memory")
; #define PG8_WAIT_L(n) asm volatile("s_waitcnt lgkmcnt(" #n ")" ::: "memory")
; #define PG8_BAR __builtin_amdgcn_s_barrier()
; #define PG8_SCHED __builtin_amdgcn_sched_barrier(0)
; template <class Epi, class Sched, bool ALIGN_EPI = false, bool SP2 = false>
; __device__ __forceinline__ void gemm_phase(PG8_LAS unsigned char* lds, const Gemm g, const Sched& S, const Epi& E) {
;     ...
;             PG8_LDB(B0, 1, 0); PG8_LDB(B1, 1, 1); PG8_SCHED; PG8_LDA(At, 1, 0); PG8_STAGE(PG8_SA(0, 0), a2, voffA); PG8_STAGE(PG8_SA(0, 1), a2 + hstep, voffA);
;             PG8_WAIT_V(8); PG8_WAIT_L(0); PG8_BAR; PG8_MMA(0, 0, At, B0); PG8_MMA(0, 1, At, B1); PG8_BAR; PG8_SCHED;
;             PG8_LDA(At, 1, 1); PG8_STAGE(PG8_SB(1, 0), b3, voffB); PG8_STAGE(PG8_SB(1, 1), b3 + hstep, voffB); (void)a3;
;             PG8_WAIT_V(6); PG8_WAIT_L(0); PG8_BAR; PG8_MMA(1, 0, At, B0); PG8_MMA(1, 1, At, B1); PG8_BAR; PG8_SCHED;
.Lpl_up:
	s_add_i32 s78, 0, 0x18000
	s_add_i32 s92, 0, 0x1c000
	v_add_u32_e32 v158, s78, v143
	v_add_u32_e32 v174, s92, v143
	ds_read_b128 v[146:149], v158
	ds_read_b128 v[150:153], v158 offset:1024
	ds_read_b128 v[154:157], v158 offset:2048
	ds_read_b128 v[158:161], v158 offset:3072
	ds_read_b128 v[162:165], v174
	ds_read_b128 v[166:169], v174 offset:1024
	ds_read_b128 v[170:173], v174 offset:2048
	ds_read_b128 v[174:177], v174 offset:3072
	s_mov_b32 m0, s37
	v_lshl_add_u64 v[232:233], s[68:69], 0, v[132:133]
	s_add_u32 s38, s68, 0x80000
	ds_read_b128 v[178:181], v145 offset:32768
	ds_read_b128 v[182:185], v145 offset:33792
	ds_read_b128 v[186:189], v145 offset:34816
	ds_read_b128 v[190:193], v145 offset:35840
	ds_read_b128 v[194:197], v145 offset:36864
	ds_read_b128 v[198:201], v145 offset:37888
	ds_read_b128 v[206:209], v145 offset:38912
	ds_read_b128 v[218:221], v145 offset:39936
	global_load_lds_dwordx4 v[232:233], off
	v_lshl_add_u64 v[232:233], s[68:69], 0, v[130:131]
	s_mov_b32 m0, s57
	s_addc_u32 s39, s69, 0
	global_load_lds_dwordx4 v[232:233], off
	v_lshl_add_u64 v[232:233], s[38:39], 0, v[132:133]
	s_mov_b32 m0, s75
	s_nop 0
	global_load_lds_dwordx4 v[232:233], off
	v_lshl_add_u64 v[232:233], s[38:39], 0, v[130:131]
	s_mov_b32 m0, s84
	s_nop 0
	global_load_lds_dwordx4 v[232:233], off
	s_waitcnt vmcnt(8)
	s_waitcnt lgkmcnt(0)
	s_barrier
	v_mfma_f32_16x16x32_bf16 v[124:127], v[146:149], v[178:181], v[124:127]
	v_mfma_f32_16x16x32_bf16 v[120:123], v[154:157], v[178:181], v[120:123]
	v_mfma_f32_16x16x32_bf16 v[108:111], v[146:149], v[186:189], v[108:111]
	v_mfma_f32_16x16x32_bf16 v[104:107], v[154:157], v[186:189], v[104:107]
	v_mfma_f32_16x16x32_bf16 v[92:95], v[146:149], v[194:197], v[92:95]
	v_mfma_f32_16x16x32_bf16 v[88:91], v[154:157], v[194:197], v[88:91]
	v_mfma_f32_16x16x32_bf16 v[76:79], v[146:149], v[206:209], v[76:79]
	v_mfma_f32_16x16x32_bf16 v[72:75], v[154:157], v[206:209], v[72:75]
	v_mfma_f32_16x16x32_bf16 v[124:127], v[150:153], v[182:185], v[124:127]
	v_mfma_f32_16x16x32_bf16 v[120:123], v[158:161], v[182:185], v[120:123]
	v_mfma_f32_16x16x32_bf16 v[108:111], v[150:153], v[190:193], v[108:111]
	v_mfma_f32_16x16x32_bf16 v[104:107], v[158:161], v[190:193], v[104:107]
	v_mfma_f32_16x16x32_bf16 v[92:95], v[150:153], v[198:201], v[92:95]
	v_mfma_f32_16x16x32_bf16 v[88:91], v[158:161], v[198:201], v[88:91]
	v_mfma_f32_16x16x32_bf16 v[76:79], v[150:153], v[218:221], v[76:79]
	v_mfma_f32_16x16x32_bf16 v[72:75], v[158:161], v[218:221], v[72:75]
	v_mfma_f32_16x16x32_bf16 v[116:119], v[162:165], v[178:181], v[116:119]
	v_mfma_f32_16x16x32_bf16 v[112:115], v[170:173], v[178:181], v[112:115]
	v_mfma_f32_16x16x32_bf16 v[100:103], v[162:165], v[186:189], v[100:103]
	v_mfma_f32_16x16x32_bf16 v[96:99], v[170:173], v[186:189], v[96:99]
	v_mfma_f32_16x16x32_bf16 v[84:87], v[162:165], v[194:197], v[84:87]
	v_mfma_f32_16x16x32_bf16 v[80:83], v[170:173], v[194:197], v[80:83]
	v_mfma_f32_16x16x32_bf16 v[68:71], v[162:165], v[206:209], v[68:71]
	v_mfma_f32_16x16x32_bf16 v[64:67], v[170:173], v[206:209], v[64:67]
	v_mfma_f32_16x16x32_bf16 v[116:119], v[166:169], v[182:185], v[116:119]
	v_mfma_f32_16x16x32_bf16 v[112:115], v[174:177], v[182:185], v[112:115]
	v_mfma_f32_16x16x32_bf16 v[100:103], v[166:169], v[190:193], v[100:103]
	v_mfma_f32_16x16x32_bf16 v[96:99], v[174:177], v[190:193], v[96:99]
	v_mfma_f32_16x16x32_bf16 v[84:87], v[166:169], v[198:201], v[84:87]
	v_mfma_f32_16x16x32_bf16 v[80:83], v[174:177], v[198:201], v[80:83]
	v_mfma_f32_16x16x32_bf16 v[68:71], v[166:169], v[218:221], v[68:71]
	v_mfma_f32_16x16x32_bf16 v[64:67], v[174:177], v[218:221], v[64:67]
	s_barrier
	s_add_i32 s38, s78, s36
	v_lshl_add_u64 v[202:203], v[202:203], 0, s[26:27]
	s_mov_b32 m0, s38
	ds_read_b128 v[178:181], v145 offset:49152
	ds_read_b128 v[182:185], v145 offset:50176
	ds_read_b128 v[186:189], v145 offset:51200
	ds_read_b128 v[190:193], v145 offset:52224
	ds_read_b128 v[194:197], v145 offset:53248
	ds_read_b128 v[198:201], v145 offset:54272
	ds_read_b128 v[206:209], v145 offset:55296
	ds_read_b128 v[218:221], v145 offset:56320
	global_load_lds_dwordx4 v[202:203], off
	s_add_i32 m0, s38, 0x2000
	s_add_u32 s10, s10, 0x80080
	v_lshl_add_u64 v[202:203], v[222:223], 0, s[26:27]
	s_addc_u32 s11, s11, 0
	s_add_i32 s38, s92, s36
	global_load_lds_dwordx4 v[202:203], off
	v_lshl_add_u64 v[202:203], s[10:11], 0, v[204:205]
	s_mov_b32 m0, s38
	s_nop 0
	global_load_lds_dwordx4 v[202:203], off
	v_lshl_add_u64 v[202:203], s[10:11], 0, v[128:129]
	s_add_i32 m0, s38, 0x2000
	s_nop 0
	global_load_lds_dwordx4 v[202:203], off
	s_waitcnt vmcnt(6)
	s_waitcnt lgkmcnt(0)
	s_barrier
	v_mfma_f32_16x16x32_bf16 v[60:63], v[146:149], v[178:181], v[60:63]
	v_mfma_f32_16x16x32_bf16 v[56:59], v[154:157], v[178:181], v[56:59]
	v_mfma_f32_16x16x32_bf16 v[44:47], v[146:149], v[186:189], v[44:47]
	v_mfma_f32_16x16x32_bf16 v[40:43], v[154:157], v[186:189], v[40:43]
	v_mfma_f32_16x16x32_bf16 v[28:31], v[146:149], v[194:197], v[28:31]
	v_mfma_f32_16x16x32_bf16 v[24:27], v[154:157], v[194:197], v[24:27]
	v_mfma_f32_16x16x32_bf16 v[12:15], v[146:149], v[206:209], v[12:15]
	v_mfma_f32_16x16x32_bf16 v[8:11], v[154:157], v[206:209], v[8:11]
	v_mfma_f32_16x16x32_bf16 v[60:63], v[150:153], v[182:185], v[60:63]
	v_mfma_f32_16x16x32_bf16 v[56:59], v[158:161], v[182:185], v[56:59]
	v_mfma_f32_16x16x32_bf16 v[44:47], v[150:153], v[190:193], v[44:47]
	v_mfma_f32_16x16x32_bf16 v[40:43], v[158:161], v[190:193], v[40:43]
	v_mfma_f32_16x16x32_bf16 v[28:31], v[150:153], v[198:201], v[28:31]
	v_mfma_f32_16x16x32_bf16 v[24:27], v[158:161], v[198:201], v[24:27]
	v_mfma_f32_16x16x32_bf16 v[12:15], v[150:153], v[218:221], v[12:15]
	v_mfma_f32_16x16x32_bf16 v[8:11], v[158:161], v[218:221], v[8:11]
	v_mfma_f32_16x16x32_bf16 v[52:55], v[162:165], v[178:181], v[52:55]
	v_mfma_f32_16x16x32_bf16 v[48:51], v[170:173], v[178:181], v[48:51]
	v_mfma_f32_16x16x32_bf16 v[36:39], v[162:165], v[186:189], v[36:39]
	v_mfma_f32_16x16x32_bf16 v[32:35], v[170:173], v[186:189], v[32:35]
	v_mfma_f32_16x16x32_bf16 v[20:23], v[162:165], v[194:197], v[20:23]
	v_mfma_f32_16x16x32_bf16 v[16:19], v[170:173], v[194:197], v[16:19]
	v_mfma_f32_16x16x32_bf16 v[4:7], v[162:165], v[206:209], v[4:7]
	v_mfma_f32_16x16x32_bf16 v[0:3], v[170:173], v[206:209], v[0:3]
	v_mfma_f32_16x16x32_bf16 v[52:55], v[166:169], v[182:185], v[52:55]
	v_mfma_f32_16x16x32_bf16 v[48:51], v[174:177], v[182:185], v[48:51]
	v_mfma_f32_16x16x32_bf16 v[36:39], v[166:169], v[190:193], v[36:39]
	v_mfma_f32_16x16x32_bf16 v[32:35], v[174:177], v[190:193], v[32:35]
	v_mfma_f32_16x16x32_bf16 v[20:23], v[166:169], v[198:201], v[20:23]
	v_mfma_f32_16x16x32_bf16 v[16:19], v[174:177], v[198:201], v[16:19]
	v_mfma_f32_16x16x32_bf16 v[4:7], v[166:169], v[218:221], v[4:7]
	v_mfma_f32_16x16x32_bf16 v[0:3], v[174:177], v[218:221], v[0:3]
	s_barrier
	s_add_i32 s53, s53, 2
	s_add_u32 vcc_lo, vcc_lo, 0x100
	s_addc_u32 vcc_hi, vcc_hi, 0
	s_cmp_gt_u32 s53, 29
	s_cbranch_scc0 .LBB0_605
	s_and_b64 vcc, exec, s[4:5]
	s_cbranch_vccz .LBB0_608
	s_barrier

; #define PG8_STAGE(bufoff, gbase, voff) do { _Pragma("unroll") for (int _i = 0; _i < 2; ++_i) \
;         __builtin_amdgcn_global_load_lds((const unsigned*)((const char*)(gbase) + (voff)[_i]), (PG8_LAS unsigned*)(lds + (bufoff) + ldsw + _i * 8192), 16, 0, 0); } while (0)
; #define PG8_LDA(dst, b, h) do { _Pragma("unroll") for (int m = 0; m < 4; ++m) _Pragma("unroll") for (int k = 0; k < 2; ++k) dst[m][k] = *(const PG8_LAS bf16x8*)(lds + PG8_SA(b, h) + aoff + m * 2048 + k * 1024); } while (0)
; #define PG8_LDB(dst, b, h) do { _Pragma("unroll") for (int n = 0; n < 2; ++n) _Pragma("unroll") for (int k = 0; k < 2; ++k) dst[n][k] = *(const PG8_LAS bf16x8*)(lds + PG8_SB(b, h) + boff + n * 2048 + k * 1024); } while (0)
; #define PG8_MMA(ai, bj, At, Bt) do { __builtin_amdgcn_s_setprio(1); _Pragma("unroll") for (int m = 0; m < 4; ++m) _Pragma("unroll") for (int n = 0; n < 2; ++n) _Pragma("unroll") for (int k = 0; k < 2; ++k) \
;         acc[ai][bj][m][n] = __builtin_amdgcn_mfma_f32_16x16x32_bf16(Bt[n][k], At[m][k], acc[ai][bj][m][n], 0, 0, 0); __builtin_amdgcn_s_setprio(0); } while (0)
; #define PG8_WAIT_V(n) asm volatile("s_waitcnt vmcnt(" #n ")" ::: "memory")
; #define PG8_WAIT_L(n) asm volatile("s_waitcnt lgkmcnt(" #n ")" ::: "memory")
; template <class Epi, class Sched, bool ALIGN_EPI = false, bool SP2 = false>
; __device__ __forceinline__ void gemm_phase(PG8_LAS unsigned char* lds, const Gemm g, const Sched& S, const Epi& E) {
;     ...
;         const bool has_next = S.next(ui + 1, nxt);
;         const char* nA = has_next ? (const char*)g.A + (size_t)nxt.pm * tstep : cA; const char* nB = has_next ? (const char*)g.Bt + (size_t)nxt.pn * tstep : cB;
;         for (int t = 0; t < nt; t += 2) {
;             const bool last = (t == nt - 2);
;             const char* a1 = cA + (size_t)(t + 1) * kstep;
;             const char* a2 = last ? nA : cA + (size_t)(t + 2) * kstep; const char* b2 = last ? nB : cB + (size_t)(t + 2) * kstep;
;             const char* a3 = a2 + kstep; const char* b3 = b2 + kstep;
;             if (last && has_next) S.a_ready(nxt);
;             if constexpr (SP2) {
;             PG8_LDB(B0, 0, 0); PG8_LDB(B1, 0, 1); PG8_SCHED; PG8_LDA(At, 0, 0); PG8_STAGE(PG8_SA(1, 0), a1, voffA); PG8_STAGE(PG8_SA(1, 1), a1 + hstep, voffA);
;             PG8_WAIT_V(8); PG8_WAIT_L(0); PG8_BAR; PG8_MMA(0, 0, At, B0); PG8_MMA(0, 1, At, B1); PG8_BAR; PG8_SCHED;
.LBB0_701:
	s_ashr_i32 s47, s46, 31
	s_lshl_b64 s[38:39], s[46:47], 22
	s_add_u32 s72, s20, s38
	s_addc_u32 s73, s21, s39
	s_and_b64 s[38:39], s[40:41], exec
	s_cselect_b32 s47, s73, s17
	s_cselect_b32 s70, s72, s16
	s_ashr_i32 s43, s42, 31
	s_lshl_b64 s[38:39], s[42:43], 22
	s_add_u32 s76, s23, s38
	s_addc_u32 s77, s34, s39
	s_and_b64 s[38:39], s[40:41], exec
	s_cselect_b32 s43, s77, s45
	s_cselect_b32 s71, s76, s44
	s_add_u32 s97, s44, 0x100
	s_addc_u32 vcc_lo, s45, 0
	v_lshl_add_u64 v[138:139], s[16:17], 0, v[134:135]
	v_lshl_add_u64 v[140:141], s[16:17], 0, v[136:137]
	s_mov_b32 s52, -2
	s_mov_b64 s[88:89], 0
	s_add_u32 s38, s16, s88
	s_addc_u32 s39, s17, s89
	s_add_u32 s38, s38, 0x100
	s_addc_u32 s39, s39, 0
	s_add_u32 s44, s97, s88
	s_addc_u32 s45, vcc_lo, s89
	s_add_i32 s53, 0, 0x10000
	s_cmpk_eq_i32 s88, 0x3f00
	s_cselect_b32 s45, s43, s45
	s_cselect_b32 s44, s71, s44
	s_cselect_b32 s69, s47, s39
	s_cselect_b32 s68, s70, s38
	s_add_i32 s78, 0, 0x14000
	v_add_u32_e32 v158, s53, v143
	v_add_u32_e32 v174, s78, v143
	ds_read_b128 v[146:149], v158
	ds_read_b128 v[150:153], v158 offset:1024
	ds_read_b128 v[154:157], v158 offset:2048
	ds_read_b128 v[158:161], v158 offset:3072
	ds_read_b128 v[162:165], v174
	ds_read_b128 v[166:169], v174 offset:1024
	ds_read_b128 v[170:173], v174 offset:2048
	ds_read_b128 v[174:177], v174 offset:3072
	v_lshl_add_u64 v[202:203], v[138:139], 0, s[88:89]
	v_lshl_add_u64 v[222:223], v[202:203], 0, s[26:27]
	s_add_i32 m0, s36, 0x8000
	ds_read_b128 v[178:181], v145
	ds_read_b128 v[182:185], v145 offset:1024
	ds_read_b128 v[186:189], v145 offset:2048
	ds_read_b128 v[190:193], v145 offset:3072
	ds_read_b128 v[194:197], v145 offset:4096
	ds_read_b128 v[198:201], v145 offset:5120
	ds_read_b128 v[206:209], v145 offset:6144
	ds_read_b128 v[218:221], v145 offset:7168
	global_load_lds_dwordx4 v[222:223], off
	v_lshl_add_u64 v[222:223], v[140:141], 0, s[88:89]
	v_lshl_add_u64 v[232:233], v[222:223], 0, s[26:27]
	s_add_i32 m0, s36, 0xa000
	v_lshl_add_u64 v[202:203], v[202:203], 0, s[90:91]
	global_load_lds_dwordx4 v[232:233], off
	s_add_i32 m0, s36, 0xc000
	s_nop 0
	global_load_lds_dwordx4 v[202:203], off
	v_lshl_add_u64 v[202:203], v[222:223], 0, s[90:91]
	s_add_i32 m0, s36, 0xe000
	s_nop 0
	global_load_lds_dwordx4 v[202:203], off
	s_waitcnt vmcnt(8)
	s_waitcnt lgkmcnt(0)
	s_barrier
	v_mfma_f32_16x16x32_bf16 v[124:127], v[146:149], v[178:181], 0
	v_mfma_f32_16x16x32_bf16 v[120:123], v[154:157], v[178:181], 0
	v_mfma_f32_16x16x32_bf16 v[116:119], v[146:149], v[186:189], 0
	v_mfma_f32_16x16x32_bf16 v[108:111], v[154:157], v[186:189], 0
	v_mfma_f32_16x16x32_bf16 v[100:103], v[146:149], v[194:197], 0
	v_mfma_f32_16x16x32_bf16 v[92:95], v[154:157], v[194:197], 0
	v_mfma_f32_16x16x32_bf16 v[84:87], v[146:149], v[206:209], 0
	v_mfma_f32_16x16x32_bf16 v[76:79], v[154:157], v[206:209], 0
	v_mfma_f32_16x16x32_bf16 v[124:127], v[150:153], v[182:185], v[124:127]
	v_mfma_f32_16x16x32_bf16 v[120:123], v[158:161], v[182:185], v[120:123]
	v_mfma_f32_16x16x32_bf16 v[116:119], v[150:153], v[190:193], v[116:119]
	v_mfma_f32_16x16x32_bf16 v[108:111], v[158:161], v[190:193], v[108:111]
	v_mfma_f32_16x16x32_bf16 v[100:103], v[150:153], v[198:201], v[100:103]
	v_mfma_f32_16x16x32_bf16 v[92:95], v[158:161], v[198:201], v[92:95]
	v_mfma_f32_16x16x32_bf16 v[84:87], v[150:153], v[218:221], v[84:87]
	v_mfma_f32_16x16x32_bf16 v[76:79], v[158:161], v[218:221], v[76:79]
	v_mfma_f32_16x16x32_bf16 v[112:115], v[162:165], v[178:181], 0
	v_mfma_f32_16x16x32_bf16 v[104:107], v[170:173], v[178:181], 0
	v_mfma_f32_16x16x32_bf16 v[96:99], v[162:165], v[186:189], 0
	v_mfma_f32_16x16x32_bf16 v[88:91], v[170:173], v[186:189], 0
	v_mfma_f32_16x16x32_bf16 v[80:83], v[162:165], v[194:197], 0
	v_mfma_f32_16x16x32_bf16 v[72:75], v[170:173], v[194:197], 0
	v_mfma_f32_16x16x32_bf16 v[68:71], v[162:165], v[206:209], 0
	v_mfma_f32_16x16x32_bf16 v[64:67], v[170:173], v[206:209], 0
	v_mfma_f32_16x16x32_bf16 v[112:115], v[166:169], v[182:185], v[112:115]
	v_mfma_f32_16x16x32_bf16 v[104:107], v[174:177], v[182:185], v[104:107]
	v_mfma_f32_16x16x32_bf16 v[96:99], v[166:169], v[190:193], v[96:99]
	v_mfma_f32_16x16x32_bf16 v[88:91], v[174:177], v[190:193], v[88:91]
	v_mfma_f32_16x16x32_bf16 v[80:83], v[166:169], v[198:201], v[80:83]
	v_mfma_f32_16x16x32_bf16 v[72:75], v[174:177], v[198:201], v[72:75]
	v_mfma_f32_16x16x32_bf16 v[68:71], v[166:169], v[218:221], v[68:71]
	v_mfma_f32_16x16x32_bf16 v[64:67], v[174:177], v[218:221], v[64:67]
	s_barrier
; #define PG8_STAGE(bufoff, gbase, voff) do { _Pragma("unroll") for (int _i = 0; _i < 2; ++_i) \
;         __builtin_amdgcn_global_load_lds((const unsigned*)((const char*)(gbase) + (voff)[_i]), (PG8_LAS unsigned*)(lds + (bufoff) + ldsw + _i * 8192), 16, 0, 0); } while (0)
; #define PG8_LDA(dst, b, h) do { _Pragma("unroll") for (int m = 0; m < 4; ++m) _Pragma("unroll") for (int k = 0; k < 2; ++k) dst[m][k] = *(const PG8_LAS bf16x8*)(lds + PG8_SA(b, h) + aoff + m * 2048 + k * 1024); } while (0)
; #define PG8_MMA(ai, bj, At, Bt) do { __builtin_amdgcn_s_setprio(1); _Pragma("unroll") for (int m = 0; m < 4; ++m) _Pragma("unroll") for (int n = 0; n < 2; ++n) _Pragma("unroll") for (int k = 0; k < 2; ++k) \
;         acc[ai][bj][m][n] = __builtin_amdgcn_mfma_f32_16x16x32_bf16(Bt[n][k], At[m][k], acc[ai][bj][m][n], 0, 0, 0); __builtin_amdgcn_s_setprio(0); } while (0)
; #define PG8_WAIT_V(n) asm volatile("s_waitcnt vmcnt(" #n ")" ::: "memory")
; #define PG8_WAIT_L(n) asm volatile("s_waitcnt lgkmcnt(" #n ")" ::: "memory")
; #define PG8_BAR __builtin_amdgcn_s_barrier()
; #define PG8_SCHED __builtin_amdgcn_sched_barrier(0)
; template <class Epi, class Sched, bool ALIGN_EPI = false, bool SP2 = false>
; __device__ __forceinline__ void gemm_phase(PG8_LAS unsigned char* lds, const Gemm g, const Sched& S, const Epi& E) {
;     ...
;             PG8_LDA(At, 0, 1); PG8_STAGE(PG8_SB(0, 0), b2, voffB); PG8_STAGE(PG8_SB(0, 1), b2 + hstep, voffB);
;             PG8_WAIT_V(6); PG8_WAIT_L(0); PG8_BAR; PG8_MMA(1, 0, At, B0); PG8_MMA(1, 1, At, B1); PG8_BAR; PG8_SCHED;
	s_add_i32 s38, s53, s35
	v_lshl_add_u64 v[202:203], s[44:45], 0, v[204:205]
	s_mov_b32 m0, s38
	ds_read_b128 v[178:181], v145 offset:16384
	ds_read_b128 v[182:185], v145 offset:17408
	ds_read_b128 v[186:189], v145 offset:18432
	ds_read_b128 v[190:193], v145 offset:19456
	ds_read_b128 v[194:197], v145 offset:20480
	ds_read_b128 v[198:201], v145 offset:21504
	ds_read_b128 v[206:209], v145 offset:22528
	ds_read_b128 v[218:221], v145 offset:23552
	global_load_lds_dwordx4 v[202:203], off
	s_add_i32 m0, s38, 0x2000
	s_add_u32 s38, s44, 0x200000
	v_lshl_add_u64 v[222:223], s[44:45], 0, v[128:129]
	s_addc_u32 s39, s45, 0
	s_add_i32 s53, s78, s35
	global_load_lds_dwordx4 v[222:223], off
	v_lshl_add_u64 v[232:233], s[38:39], 0, v[204:205]
	s_mov_b32 m0, s53
	s_nop 0
	global_load_lds_dwordx4 v[232:233], off
	v_lshl_add_u64 v[232:233], s[38:39], 0, v[128:129]
	s_add_i32 m0, s53, 0x2000
	s_nop 0
	global_load_lds_dwordx4 v[232:233], off
	s_waitcnt vmcnt(6)
	s_waitcnt lgkmcnt(0)
	s_barrier
	v_mfma_f32_16x16x32_bf16 v[60:63], v[146:149], v[178:181], 0
	v_mfma_f32_16x16x32_bf16 v[56:59], v[154:157], v[178:181], 0
	v_mfma_f32_16x16x32_bf16 v[52:55], v[146:149], v[186:189], 0
	v_mfma_f32_16x16x32_bf16 v[44:47], v[154:157], v[186:189], 0
	v_mfma_f32_16x16x32_bf16 v[36:39], v[146:149], v[194:197], 0
	v_mfma_f32_16x16x32_bf16 v[28:31], v[154:157], v[194:197], 0
	v_mfma_f32_16x16x32_bf16 v[20:23], v[146:149], v[206:209], 0
	v_mfma_f32_16x16x32_bf16 v[12:15], v[154:157], v[206:209], 0
	v_mfma_f32_16x16x32_bf16 v[60:63], v[150:153], v[182:185], v[60:63]
	v_mfma_f32_16x16x32_bf16 v[56:59], v[158:161], v[182:185], v[56:59]
	v_mfma_f32_16x16x32_bf16 v[52:55], v[150:153], v[190:193], v[52:55]
	v_mfma_f32_16x16x32_bf16 v[44:47], v[158:161], v[190:193], v[44:47]
	v_mfma_f32_16x16x32_bf16 v[36:39], v[150:153], v[198:201], v[36:39]
	v_mfma_f32_16x16x32_bf16 v[28:31], v[158:161], v[198:201], v[28:31]
	v_mfma_f32_16x16x32_bf16 v[20:23], v[150:153], v[218:221], v[20:23]
	v_mfma_f32_16x16x32_bf16 v[12:15], v[158:161], v[218:221], v[12:15]
	v_mfma_f32_16x16x32_bf16 v[48:51], v[162:165], v[178:181], 0
	v_mfma_f32_16x16x32_bf16 v[40:43], v[170:173], v[178:181], 0
	v_mfma_f32_16x16x32_bf16 v[32:35], v[162:165], v[186:189], 0
	v_mfma_f32_16x16x32_bf16 v[24:27], v[170:173], v[186:189], 0
	v_mfma_f32_16x16x32_bf16 v[16:19], v[162:165], v[194:197], 0
	v_mfma_f32_16x16x32_bf16 v[8:11], v[170:173], v[194:197], 0
	v_mfma_f32_16x16x32_bf16 v[4:7], v[162:165], v[206:209], 0
	v_mfma_f32_16x16x32_bf16 v[0:3], v[170:173], v[206:209], 0
	v_mfma_f32_16x16x32_bf16 v[48:51], v[166:169], v[182:185], v[48:51]
	v_mfma_f32_16x16x32_bf16 v[40:43], v[174:177], v[182:185], v[40:43]
	v_mfma_f32_16x16x32_bf16 v[32:35], v[166:169], v[190:193], v[32:35]
	v_mfma_f32_16x16x32_bf16 v[24:27], v[174:177], v[190:193], v[24:27]
	v_mfma_f32_16x16x32_bf16 v[16:19], v[166:169], v[198:201], v[16:19]
	v_mfma_f32_16x16x32_bf16 v[8:11], v[174:177], v[198:201], v[8:11]
	v_mfma_f32_16x16x32_bf16 v[4:7], v[166:169], v[218:221], v[4:7]
	v_mfma_f32_16x16x32_bf16 v[0:3], v[174:177], v[218:221], v[0:3]
	s_barrier
	s_branch .Lpl_down

; #define PG8_STAGE(bufoff, gbase, voff) do { _Pragma("unroll") for (int _i = 0; _i < 2; ++_i) \
;         __builtin_amdgcn_global_load_lds((const unsigned*)((const char*)(gbase) + (voff)[_i]), (PG8_LAS unsigned*)(lds + (bufoff) + ldsw + _i * 8192), 16, 0, 0); } while (0)
; #define PG8_LDA(dst, b, h) do { _Pragma("unroll") for (int m = 0; m < 4; ++m) _Pragma("unroll") for (int k = 0; k < 2; ++k) dst[m][k] = *(const PG8_LAS bf16x8*)(lds + PG8_SA(b, h) + aoff + m * 2048 + k * 1024); } while (0)
; #define PG8_LDB(dst, b, h) do { _Pragma("unroll") for (int n = 0; n < 2; ++n) _Pragma("unroll") for (int k = 0; k < 2; ++k) dst[n][k] = *(const PG8_LAS bf16x8*)(lds + PG8_SB(b, h) + boff + n * 2048 + k * 1024); } while (0)
; #define PG8_MMA(ai, bj, At, Bt) do { __builtin_amdgcn_s_setprio(1); _Pragma("unroll") for (int m = 0; m < 4; ++m) _Pragma("unroll") for (int n = 0; n < 2; ++n) _Pragma("unroll") for (int k = 0; k < 2; ++k) \
;         acc[ai][bj][m][n] = __builtin_amdgcn_mfma_f32_16x16x32_bf16(Bt[n][k], At[m][k], acc[ai][bj][m][n], 0, 0, 0); __builtin_amdgcn_s_setprio(0); } while (0)
; #define PG8_WAIT_V(n) asm volatile("s_waitcnt vmcnt(" #n ")" ::: "memory")
; #define PG8_WAIT_L(n) asm volatile("s_waitcnt lgkmcnt(" #n ")" ::: "memory")
; #define PG8_BAR __builtin_amdgcn_s_barrier()
; #define PG8_SCHED __builtin_amdgcn_sched_barrier(0)
; template <class Epi, class Sched, bool ALIGN_EPI = false, bool SP2 = false>
; __device__ __forceinline__ void gemm_phase(PG8_LAS unsigned char* lds, const Gemm g, const Sched& S, const Epi& E) {
;     ...
;             PG8_LDB(B0, 1, 0); PG8_LDB(B1, 1, 1); PG8_SCHED; PG8_LDA(At, 1, 0); PG8_STAGE(PG8_SA(0, 0), a2, voffA); PG8_STAGE(PG8_SA(0, 1), a2 + hstep, voffA);
;             PG8_WAIT_V(8); PG8_WAIT_L(0); PG8_BAR; PG8_MMA(0, 0, At, B0); PG8_MMA(0, 1, At, B1); PG8_BAR; PG8_SCHED;
;             PG8_LDA(At, 1, 1); PG8_STAGE(PG8_SB(1, 0), b3, voffB); PG8_STAGE(PG8_SB(1, 1), b3 + hstep, voffB); (void)a3;
;             PG8_WAIT_V(6); PG8_WAIT_L(0); PG8_BAR; PG8_MMA(1, 0, At, B0); PG8_MMA(1, 1, At, B1); PG8_BAR; PG8_SCHED;
.Lpl_down:
	s_add_i32 s53, 0, 0x18000
	s_add_i32 s78, 0, 0x1c000
	v_add_u32_e32 v158, s53, v143
	v_add_u32_e32 v174, s78, v143
	ds_read_b128 v[146:149], v158
	ds_read_b128 v[150:153], v158 offset:1024
	ds_read_b128 v[154:157], v158 offset:2048
	ds_read_b128 v[158:161], v158 offset:3072
	ds_read_b128 v[162:165], v174
	ds_read_b128 v[166:169], v174 offset:1024
	ds_read_b128 v[170:173], v174 offset:2048
	ds_read_b128 v[174:177], v174 offset:3072
	s_mov_b32 m0, s36
	v_lshl_add_u64 v[232:233], s[68:69], 0, v[132:133]
	s_add_u32 s38, s68, 0x200000
	ds_read_b128 v[178:181], v145 offset:32768
	ds_read_b128 v[182:185], v145 offset:33792
	ds_read_b128 v[186:189], v145 offset:34816
	ds_read_b128 v[190:193], v145 offset:35840
	ds_read_b128 v[194:197], v145 offset:36864
	ds_read_b128 v[198:201], v145 offset:37888
	ds_read_b128 v[206:209], v145 offset:38912
	ds_read_b128 v[218:221], v145 offset:39936
	global_load_lds_dwordx4 v[232:233], off
	v_lshl_add_u64 v[232:233], s[68:69], 0, v[130:131]
	s_mov_b32 m0, s37
	s_addc_u32 s39, s69, 0
	global_load_lds_dwordx4 v[232:233], off
	v_lshl_add_u64 v[232:233], s[38:39], 0, v[132:133]
	s_mov_b32 m0, s57
	s_nop 0
	global_load_lds_dwordx4 v[232:233], off
	v_lshl_add_u64 v[232:233], s[38:39], 0, v[130:131]
	s_mov_b32 m0, s75
	s_nop 0
	global_load_lds_dwordx4 v[232:233], off
	s_waitcnt vmcnt(8)
	s_waitcnt lgkmcnt(0)
	s_barrier
	v_mfma_f32_16x16x32_bf16 v[124:127], v[146:149], v[178:181], v[124:127]
	v_mfma_f32_16x16x32_bf16 v[120:123], v[154:157], v[178:181], v[120:123]
	v_mfma_f32_16x16x32_bf16 v[116:119], v[146:149], v[186:189], v[116:119]
	v_mfma_f32_16x16x32_bf16 v[108:111], v[154:157], v[186:189], v[108:111]
	v_mfma_f32_16x16x32_bf16 v[100:103], v[146:149], v[194:197], v[100:103]
	v_mfma_f32_16x16x32_bf16 v[92:95], v[154:157], v[194:197], v[92:95]
	v_mfma_f32_16x16x32_bf16 v[84:87], v[146:149], v[206:209], v[84:87]
	v_mfma_f32_16x16x32_bf16 v[76:79], v[154:157], v[206:209], v[76:79]
	v_mfma_f32_16x16x32_bf16 v[124:127], v[150:153], v[182:185], v[124:127]
	v_mfma_f32_16x16x32_bf16 v[120:123], v[158:161], v[182:185], v[120:123]
	v_mfma_f32_16x16x32_bf16 v[116:119], v[150:153], v[190:193], v[116:119]
	v_mfma_f32_16x16x32_bf16 v[108:111], v[158:161], v[190:193], v[108:111]
	v_mfma_f32_16x16x32_bf16 v[100:103], v[150:153], v[198:201], v[100:103]
	v_mfma_f32_16x16x32_bf16 v[92:95], v[158:161], v[198:201], v[92:95]
	v_mfma_f32_16x16x32_bf16 v[84:87], v[150:153], v[218:221], v[84:87]
	v_mfma_f32_16x16x32_bf16 v[76:79], v[158:161], v[218:221], v[76:79]
	v_mfma_f32_16x16x32_bf16 v[112:115], v[162:165], v[178:181], v[112:115]
	v_mfma_f32_16x16x32_bf16 v[104:107], v[170:173], v[178:181], v[104:107]
	v_mfma_f32_16x16x32_bf16 v[96:99], v[162:165], v[186:189], v[96:99]
	v_mfma_f32_16x16x32_bf16 v[88:91], v[170:173], v[186:189], v[88:91]
	v_mfma_f32_16x16x32_bf16 v[80:83], v[162:165], v[194:197], v[80:83]
	v_mfma_f32_16x16x32_bf16 v[72:75], v[170:173], v[194:197], v[72:75]
	v_mfma_f32_16x16x32_bf16 v[68:71], v[162:165], v[206:209], v[68:71]
	v_mfma_f32_16x16x32_bf16 v[64:67], v[170:173], v[206:209], v[64:67]
	v_mfma_f32_16x16x32_bf16 v[112:115], v[166:169], v[182:185], v[112:115]
	v_mfma_f32_16x16x32_bf16 v[104:107], v[174:177], v[182:185], v[104:107]
	v_mfma_f32_16x16x32_bf16 v[96:99], v[166:169], v[190:193], v[96:99]
	v_mfma_f32_16x16x32_bf16 v[88:91], v[174:177], v[190:193], v[88:91]
	v_mfma_f32_16x16x32_bf16 v[80:83], v[166:169], v[198:201], v[80:83]
	v_mfma_f32_16x16x32_bf16 v[72:75], v[174:177], v[198:201], v[72:75]
	v_mfma_f32_16x16x32_bf16 v[68:71], v[166:169], v[218:221], v[68:71]
	v_mfma_f32_16x16x32_bf16 v[64:67], v[174:177], v[218:221], v[64:67]
	s_barrier
	s_add_i32 s38, s53, s35
	v_lshl_add_u64 v[202:203], v[202:203], 0, s[26:27]
	s_mov_b32 m0, s38
	ds_read_b128 v[178:181], v145 offset:49152
	ds_read_b128 v[182:185], v145 offset:50176
	ds_read_b128 v[186:189], v145 offset:51200
	ds_read_b128 v[190:193], v145 offset:52224
	ds_read_b128 v[194:197], v145 offset:53248
	ds_read_b128 v[198:201], v145 offset:54272
	ds_read_b128 v[206:209], v145 offset:55296
	ds_read_b128 v[218:221], v145 offset:56320
	global_load_lds_dwordx4 v[202:203], off
	s_add_i32 m0, s38, 0x2000
	s_add_u32 s38, s44, 0x200080
	v_lshl_add_u64 v[202:203], v[222:223], 0, s[26:27]
	s_addc_u32 s39, s45, 0
	s_add_i32 s44, s78, s35
	global_load_lds_dwordx4 v[202:203], off
	v_lshl_add_u64 v[202:203], s[38:39], 0, v[204:205]
	s_mov_b32 m0, s44
	s_nop 0
	global_load_lds_dwordx4 v[202:203], off
	v_lshl_add_u64 v[202:203], s[38:39], 0, v[128:129]
	s_add_i32 m0, s44, 0x2000
	s_nop 0
	global_load_lds_dwordx4 v[202:203], off
	s_waitcnt vmcnt(6)
	s_waitcnt lgkmcnt(0)
	s_barrier
	v_mfma_f32_16x16x32_bf16 v[60:63], v[146:149], v[178:181], v[60:63]
	v_mfma_f32_16x16x32_bf16 v[56:59], v[154:157], v[178:181], v[56:59]
	v_mfma_f32_16x16x32_bf16 v[52:55], v[146:149], v[186:189], v[52:55]
	v_mfma_f32_16x16x32_bf16 v[44:47], v[154:157], v[186:189], v[44:47]
	v_mfma_f32_16x16x32_bf16 v[36:39], v[146:149], v[194:197], v[36:39]
	v_mfma_f32_16x16x32_bf16 v[28:31], v[154:157], v[194:197], v[28:31]
	v_mfma_f32_16x16x32_bf16 v[20:23], v[146:149], v[206:209], v[20:23]
	v_mfma_f32_16x16x32_bf16 v[12:15], v[154:157], v[206:209], v[12:15]
	v_mfma_f32_16x16x32_bf16 v[60:63], v[150:153], v[182:185], v[60:63]
	v_mfma_f32_16x16x32_bf16 v[56:59], v[158:161], v[182:185], v[56:59]
	v_mfma_f32_16x16x32_bf16 v[52:55], v[150:153], v[190:193], v[52:55]
	v_mfma_f32_16x16x32_bf16 v[44:47], v[158:161], v[190:193], v[44:47]
	v_mfma_f32_16x16x32_bf16 v[36:39], v[150:153], v[198:201], v[36:39]
	v_mfma_f32_16x16x32_bf16 v[28:31], v[158:161], v[198:201], v[28:31]
	v_mfma_f32_16x16x32_bf16 v[20:23], v[150:153], v[218:221], v[20:23]
	v_mfma_f32_16x16x32_bf16 v[12:15], v[158:161], v[218:221], v[12:15]
	v_mfma_f32_16x16x32_bf16 v[48:51], v[162:165], v[178:181], v[48:51]
	v_mfma_f32_16x16x32_bf16 v[40:43], v[170:173], v[178:181], v[40:43]
	v_mfma_f32_16x16x32_bf16 v[32:35], v[162:165], v[186:189], v[32:35]
	v_mfma_f32_16x16x32_bf16 v[24:27], v[170:173], v[186:189], v[24:27]
	v_mfma_f32_16x16x32_bf16 v[16:19], v[162:165], v[194:197], v[16:19]
	v_mfma_f32_16x16x32_bf16 v[8:11], v[170:173], v[194:197], v[8:11]
	v_mfma_f32_16x16x32_bf16 v[4:7], v[162:165], v[206:209], v[4:7]
	v_mfma_f32_16x16x32_bf16 v[0:3], v[170:173], v[206:209], v[0:3]
	v_mfma_f32_16x16x32_bf16 v[48:51], v[166:169], v[182:185], v[48:51]
	v_mfma_f32_16x16x32_bf16 v[40:43], v[174:177], v[182:185], v[40:43]
	v_mfma_f32_16x16x32_bf16 v[32:35], v[166:169], v[190:193], v[32:35]
	v_mfma_f32_16x16x32_bf16 v[24:27], v[174:177], v[190:193], v[24:27]
	v_mfma_f32_16x16x32_bf16 v[16:19], v[166:169], v[198:201], v[16:19]
	v_mfma_f32_16x16x32_bf16 v[8:11], v[174:177], v[198:201], v[8:11]
	v_mfma_f32_16x16x32_bf16 v[4:7], v[166:169], v[218:221], v[4:7]
	v_mfma_f32_16x16x32_bf16 v[0:3], v[174:177], v[218:221], v[0:3]
	s_barrier
	s_add_i32 s52, s52, 2
	s_add_u32 s88, s88, 0x100
	s_addc_u32 s89, s89, 0
	s_cmpk_gt_u32 s52, 0x7d
	s_cbranch_scc0 .LBB0_702
	s_and_b64 vcc, exec, s[10:11]
	s_cbranch_vccz .LBB0_705
	s_barrier
